# K-loops VALU-free: B-fragment LDS addresses from one hoisted base register with immediate offsets, F2 m0 temp renamed so all DMAs use saddr form; accumulator zeroing with 64-bit moves; on top of v41
# speedup vs baseline: 1.0051x; 1.0030x over previous
;     __host__ __device__ bool next(int i, Unit& u) const { const long L = (long)i * G + c; if (L >= lim) return false; unit_of((int)L, u); return true; }
;     __device__ __forceinline__ bool next(int i, Unit& v) const { if (i != 0) return false; v = u; return true; }
; #define PG8_STAGE(bufoff, gbase, voff) do { _Pragma("unroll") for (int _i = 0; _i < 2; ++_i) \
;         __builtin_amdgcn_global_load_lds((const unsigned*)((const char*)(gbase) + (voff)[_i]), (PG8_LAS unsigned*)(lds + (bufoff) + ldsw + _i * 8192), 16, 0, 0); } while (0)
; #define PG8_LDA(dst, b, h) do { _Pragma("unroll") for (int m = 0; m < 4; ++m) _Pragma("unroll") for (int k = 0; k < 2; ++k) dst[m][k] = *(const PG8_LAS bf16x8*)(lds + PG8_SA(b, h) + aoff + m * 2048 + k * 1024); } while (0)
; #define PG8_WAIT_L(n) asm volatile("s_waitcnt lgkmcnt(" #n ")" ::: "memory")
;     ...
;         const bool has_next = S.next(ui + 1, nxt);
;         if constexpr (TP == 3) { if (ui > 0) tp_acc += __builtin_amdgcn_s_memrealtime() - tp3; }
;         const char* nA = has_next ? (const char*)g.A + (size_t)nxt.pm * tstep : cA; const char* nB = has_next ? (const char*)g.Bt + (size_t)nxt.pn * tstep : cB;
;         for (int t = 0; t < nt * KREP; t += 2) {
;             const bool last = (t == nt * KREP - 2);
;             const int t1w = KREP > 1 ? ((t + 1) & (nt - 1)) : t + 1, t2w = KREP > 1 ? ((t + 2) & (nt - 1)) : t + 2;
;             const char* a1 = cA + (size_t)t1w * kstep;
;             const char* a2 = last ? nA : cA + (size_t)t2w * kstep; const char* b2 = last ? nB : cB + (size_t)t2w * kstep;
;             const char* a3 = a2 + kstep; const char* b3 = b2 + kstep;
;             if (last && has_next) S.a_ready(nxt);
;             const int relax = __builtin_amdgcn_readfirstlane((MK_RELAXW && t == 0 && ui > 0) ? 1 : 0);
;             if constexpr (SP2) {
;             PG8_LDB(B0, 0, 0); PG8_LDB(B1, 0, 1); PG8_SCHED; PG8_LDA(At, 0, 0); PG8_STAGE(PG8_SA(1, 1), a1 + hstep, voffA);
;             PG8_WAIT_V_SEL(relax);
;             PG8_WAIT_L(0); PG8_BAR; PG8_MMA(0, 0, At, B0); PG8_MMA(0, 1, At, B1); PG8_BAR; PG8_SCHED;
;     ...
; #pragma unroll
;         for (int a = 0; a < 2; ++a)
; #pragma unroll
;             for (int b = 0; b < 2; ++b)
; #pragma unroll
;                 for (int m = 0; m < 4; ++m)
; #pragma unroll
;                     for (int n = 0; n < 2; ++n) acc[a][b][m][n] = (f32x4){0.f, 0.f, 0.f, 0.f};
.LBB0_233:
	s_ashr_i32 s69, s68, 31
	s_lshl_b64 s[0:1], s[68:69], 20
	s_add_u32 s70, s51, s0
	s_addc_u32 s71, s84, s1
	s_and_b64 s[0:1], s[6:7], exec
	s_cselect_b32 s19, s71, s79
	s_cselect_b32 s20, s70, s78
	s_ashr_i32 s67, s66, 31
	s_lshl_b64 s[0:1], s[66:67], 20
	s_add_u32 s72, s85, s0
	s_addc_u32 s73, s86, s1
	s_and_b64 s[0:1], s[6:7], exec
	s_cselect_b32 s24, s73, s81
	s_cselect_b32 s31, s72, s80
	s_add_u32 s78, s78, 0x80080
	s_addc_u32 s79, s79, 0
	s_add_u32 s33, s80, 0x100
	v_mov_b64_e32 v[2:3], 0
	v_mov_b64_e32 v[4:5], 0
	v_mov_b64_e32 v[6:7], 0
	v_mov_b64_e32 v[8:9], 0
	v_mov_b64_e32 v[10:11], 0
	v_mov_b64_e32 v[12:13], 0
	v_mov_b64_e32 v[14:15], 0
	v_mov_b64_e32 v[16:17], 0
	v_mov_b64_e32 v[18:19], 0
	v_mov_b64_e32 v[20:21], 0
	v_mov_b64_e32 v[22:23], 0
	v_mov_b64_e32 v[24:25], 0
	v_mov_b64_e32 v[26:27], 0
	v_mov_b64_e32 v[28:29], 0
	v_mov_b64_e32 v[30:31], 0
	v_mov_b64_e32 v[32:33], 0
	v_mov_b64_e32 v[34:35], 0
	v_mov_b64_e32 v[36:37], 0
	v_mov_b64_e32 v[38:39], 0
	v_mov_b64_e32 v[40:41], 0
	v_mov_b64_e32 v[42:43], 0
	v_mov_b64_e32 v[44:45], 0
	v_mov_b64_e32 v[46:47], 0
	v_mov_b64_e32 v[48:49], 0
	v_mov_b64_e32 v[50:51], 0
	v_mov_b64_e32 v[52:53], 0
	v_mov_b64_e32 v[54:55], 0
	v_mov_b64_e32 v[56:57], 0
	v_mov_b64_e32 v[58:59], 0
	v_mov_b64_e32 v[60:61], 0
	v_mov_b64_e32 v[62:63], 0
	v_mov_b64_e32 v[64:65], 0
	v_mov_b64_e32 v[66:67], 0
	v_mov_b64_e32 v[68:69], 0
	v_mov_b64_e32 v[70:71], 0
	v_mov_b64_e32 v[72:73], 0
	v_mov_b64_e32 v[74:75], 0
	v_mov_b64_e32 v[76:77], 0
	v_mov_b64_e32 v[78:79], 0
	v_mov_b64_e32 v[80:81], 0
	v_mov_b64_e32 v[82:83], 0
	v_mov_b64_e32 v[84:85], 0
	v_mov_b64_e32 v[86:87], 0
	v_mov_b64_e32 v[88:89], 0
	v_mov_b64_e32 v[90:91], 0
	v_mov_b64_e32 v[92:93], 0
	v_mov_b64_e32 v[94:95], 0
	v_mov_b64_e32 v[96:97], 0
	v_mov_b64_e32 v[98:99], 0
	v_mov_b64_e32 v[100:101], 0
	v_mov_b64_e32 v[102:103], 0
	v_mov_b64_e32 v[104:105], 0
	v_mov_b64_e32 v[106:107], 0
	v_mov_b64_e32 v[108:109], 0
	v_mov_b64_e32 v[110:111], 0
	v_mov_b64_e32 v[112:113], 0
	v_mov_b64_e32 v[114:115], 0
	v_mov_b64_e32 v[116:117], 0
	v_mov_b64_e32 v[118:119], 0
	v_mov_b64_e32 v[120:121], 0
	v_mov_b64_e32 v[122:123], 0
	v_mov_b64_e32 v[124:125], 0
	v_mov_b64_e32 v[126:127], 0
	v_mov_b64_e32 v[128:129], 0
	s_addc_u32 s35, s81, 0
	s_mov_b32 s37, -2
	s_waitcnt lgkmcnt(0)
	v_add_u32_e32 v168, 0x10000, v181
.LBB0_234:
	s_add_u32 s0, s78, 0xfff80080
	s_addc_u32 s1, s79, -1
	s_add_i32 s40, 0, 0x10000
	s_cmp_eq_u32 s37, 28
	s_cselect_b32 s83, s19, s1
	s_cselect_b32 s82, s20, s0
	s_cselect_b32 s81, s24, s35
	s_cselect_b32 s80, s31, s33
	s_add_i32 s41, 0, 0x14000
	ds_read_b128 v[142:145], v168
	ds_read_b128 v[146:149], v168 offset:1024
	ds_read_b128 v[150:153], v168 offset:2048
	ds_read_b128 v[154:157], v168 offset:3072
	ds_read_b128 v[158:161], v168 offset:16384
	ds_read_b128 v[162:165], v168 offset:17408
	ds_read_b128 v[174:177], v168 offset:18432
	ds_read_b128 v[188:191], v168 offset:19456
	s_add_i32 m0, s75, 0xc000
	ds_read_b128 v[198:201], v196
	ds_read_b128 v[202:205], v196 offset:1024
	ds_read_b128 v[206:209], v196 offset:2048
	ds_read_b128 v[210:213], v196 offset:3072
	ds_read_b128 v[214:217], v196 offset:4096
	ds_read_b128 v[218:221], v196 offset:5120
	ds_read_b128 v[222:225], v196 offset:6144
	ds_read_b128 v[226:229], v196 offset:7168
	global_load_lds_dwordx4 v138, s[78:79]
	s_add_i32 m0, s75, 0xe000
	s_nop 0
	global_load_lds_dwordx4 v140, s[78:79]
	s_waitcnt vmcnt(8)
	s_waitcnt lgkmcnt(0)
	s_setprio 1
	s_barrier
	v_mfma_f32_16x16x32_bf16 v[126:129], v[142:145], v[198:201], v[126:129]
	v_mfma_f32_16x16x32_bf16 v[110:113], v[150:153], v[198:201], v[110:113]
	v_mfma_f32_16x16x32_bf16 v[122:125], v[142:145], v[206:209], v[122:125]
	v_mfma_f32_16x16x32_bf16 v[106:109], v[150:153], v[206:209], v[106:109]
	v_mfma_f32_16x16x32_bf16 v[118:121], v[142:145], v[214:217], v[118:121]
	v_mfma_f32_16x16x32_bf16 v[102:105], v[150:153], v[214:217], v[102:105]
	v_mfma_f32_16x16x32_bf16 v[114:117], v[142:145], v[222:225], v[114:117]
	v_mfma_f32_16x16x32_bf16 v[98:101], v[150:153], v[222:225], v[98:101]
	v_mfma_f32_16x16x32_bf16 v[126:129], v[146:149], v[202:205], v[126:129]
	v_mfma_f32_16x16x32_bf16 v[110:113], v[154:157], v[202:205], v[110:113]
	v_mfma_f32_16x16x32_bf16 v[122:125], v[146:149], v[210:213], v[122:125]
	v_mfma_f32_16x16x32_bf16 v[106:109], v[154:157], v[210:213], v[106:109]
	v_mfma_f32_16x16x32_bf16 v[118:121], v[146:149], v[218:221], v[118:121]
	v_mfma_f32_16x16x32_bf16 v[102:105], v[154:157], v[218:221], v[102:105]
	v_mfma_f32_16x16x32_bf16 v[114:117], v[146:149], v[226:229], v[114:117]
	v_mfma_f32_16x16x32_bf16 v[98:101], v[154:157], v[226:229], v[98:101]
	v_mfma_f32_16x16x32_bf16 v[82:85], v[158:161], v[198:201], v[82:85]
	v_mfma_f32_16x16x32_bf16 v[30:33], v[174:177], v[198:201], v[30:33]
	v_mfma_f32_16x16x32_bf16 v[70:73], v[158:161], v[206:209], v[70:73]
	v_mfma_f32_16x16x32_bf16 v[26:29], v[174:177], v[206:209], v[26:29]
	v_mfma_f32_16x16x32_bf16 v[66:69], v[158:161], v[214:217], v[66:69]
	v_mfma_f32_16x16x32_bf16 v[22:25], v[174:177], v[214:217], v[22:25]
	v_mfma_f32_16x16x32_bf16 v[58:61], v[158:161], v[222:225], v[58:61]
	v_mfma_f32_16x16x32_bf16 v[18:21], v[174:177], v[222:225], v[18:21]
	v_mfma_f32_16x16x32_bf16 v[82:85], v[162:165], v[202:205], v[82:85]
	v_mfma_f32_16x16x32_bf16 v[30:33], v[188:191], v[202:205], v[30:33]
	v_mfma_f32_16x16x32_bf16 v[70:73], v[162:165], v[210:213], v[70:73]
	v_mfma_f32_16x16x32_bf16 v[26:29], v[188:191], v[210:213], v[26:29]
	v_mfma_f32_16x16x32_bf16 v[66:69], v[162:165], v[218:221], v[66:69]
	v_mfma_f32_16x16x32_bf16 v[22:25], v[188:191], v[218:221], v[22:25]
	v_mfma_f32_16x16x32_bf16 v[58:61], v[162:165], v[226:229], v[58:61]
	v_mfma_f32_16x16x32_bf16 v[18:21], v[188:191], v[226:229], v[18:21]
	s_barrier
; #define PG8_STAGE(bufoff, gbase, voff) do { _Pragma("unroll") for (int _i = 0; _i < 2; ++_i) \
;         __builtin_amdgcn_global_load_lds((const unsigned*)((const char*)(gbase) + (voff)[_i]), (PG8_LAS unsigned*)(lds + (bufoff) + ldsw + _i * 8192), 16, 0, 0); } while (0)
; #define PG8_LDA(dst, b, h) do { _Pragma("unroll") for (int m = 0; m < 4; ++m) _Pragma("unroll") for (int k = 0; k < 2; ++k) dst[m][k] = *(const PG8_LAS bf16x8*)(lds + PG8_SA(b, h) + aoff + m * 2048 + k * 1024); } while (0)
; #define PG8_LDB(dst, b, h) do { _Pragma("unroll") for (int n = 0; n < 2; ++n) _Pragma("unroll") for (int k = 0; k < 2; ++k) dst[n][k] = *(const PG8_LAS bf16x8*)(lds + PG8_SB(b, h) + boff + n * 2048 + k * 1024); } while (0)
; #define PG8_WAIT_V(n) asm volatile("s_waitcnt vmcnt(" #n ")" ::: "memory")
; #define PG8_WAIT_L(n) asm volatile("s_waitcnt lgkmcnt(" #n ")" ::: "memory")
; #define PG8_WAIT_V_SEL(sel) asm volatile("s_cmp_eq_u32 %0, 0\n\ts_cbranch_scc1 .Lw8_%=\n\ts_waitcnt vmcnt(22)\n\ts_branch .Lwd_%=\n.Lw8_%=:\n\ts_waitcnt vmcnt(8)\n.Lwd_%=:" :: "s"(sel) : "memory", "scc")
; #define PG8_BAR __builtin_amdgcn_s_barrier()
; #define PG8_SCHED __builtin_amdgcn_sched_barrier(0)
;     ...
;             PG8_LDA(At, 0, 1); PG8_STAGE(PG8_SB(0, 0), b2, voffB); PG8_STAGE(PG8_SB(0, 1), b2 + hstep, voffB); PG8_STAGE(PG8_SA(0, 0), a2, voffA);
;             PG8_WAIT_V_SEL(relax);
;             PG8_WAIT_L(0); PG8_BAR; PG8_MMA(1, 0, At, B0); PG8_MMA(1, 1, At, B1); PG8_BAR; PG8_SCHED;
;             PG8_LDB(B0, 1, 0); PG8_LDB(B1, 1, 1); PG8_SCHED; PG8_LDA(At, 1, 0); PG8_STAGE(PG8_SA(0, 1), a2 + hstep, voffA);
;             PG8_WAIT_V(8); PG8_WAIT_L(0); PG8_BAR; PG8_MMA(0, 0, At, B0); PG8_MMA(0, 1, At, B1); PG8_BAR; PG8_SCHED;
	s_setprio 0
	s_add_i32 s0, s40, s87
	s_mov_b32 m0, s0
	ds_read_b128 v[198:201], v196 offset:16384
	ds_read_b128 v[202:205], v196 offset:17408
	ds_read_b128 v[206:209], v196 offset:18432
	ds_read_b128 v[210:213], v196 offset:19456
	ds_read_b128 v[214:217], v196 offset:20480
	ds_read_b128 v[218:221], v196 offset:21504
	ds_read_b128 v[222:225], v196 offset:22528
	ds_read_b128 v[226:229], v196 offset:23552
	global_load_lds_dwordx4 v182, s[80:81]
	s_add_i32 m0, s0, 0x2000
	s_add_u32 s0, s80, 0x80000
	s_addc_u32 s1, s81, 0
	s_add_i32 s40, s41, s87
	global_load_lds_dwordx4 v134, s[80:81]
	s_mov_b32 m0, s40
	s_nop 0
	global_load_lds_dwordx4 v182, s[0:1]
	s_add_i32 m0, s40, 0x2000
	s_nop 0
	global_load_lds_dwordx4 v134, s[0:1]
	s_mov_b32 m0, s75
	s_nop 0
	global_load_lds_dwordx4 v130, s[82:83]
	s_mov_b32 m0, s88
	s_nop 0
	global_load_lds_dwordx4 v132, s[82:83]
	s_waitcnt vmcnt(8)
	s_waitcnt lgkmcnt(0)
	s_setprio 1
	s_barrier
	v_mfma_f32_16x16x32_bf16 v[94:97], v[142:145], v[198:201], v[94:97]
	v_mfma_f32_16x16x32_bf16 v[74:77], v[150:153], v[198:201], v[74:77]
	v_mfma_f32_16x16x32_bf16 v[90:93], v[142:145], v[206:209], v[90:93]
	v_mfma_f32_16x16x32_bf16 v[62:65], v[150:153], v[206:209], v[62:65]
	v_mfma_f32_16x16x32_bf16 v[86:89], v[142:145], v[214:217], v[86:89]
	v_mfma_f32_16x16x32_bf16 v[54:57], v[150:153], v[214:217], v[54:57]
	v_mfma_f32_16x16x32_bf16 v[78:81], v[142:145], v[222:225], v[78:81]
	v_mfma_f32_16x16x32_bf16 v[50:53], v[150:153], v[222:225], v[50:53]
	v_mfma_f32_16x16x32_bf16 v[94:97], v[146:149], v[202:205], v[94:97]
	v_mfma_f32_16x16x32_bf16 v[74:77], v[154:157], v[202:205], v[74:77]
	v_mfma_f32_16x16x32_bf16 v[90:93], v[146:149], v[210:213], v[90:93]
	v_mfma_f32_16x16x32_bf16 v[62:65], v[154:157], v[210:213], v[62:65]
	v_mfma_f32_16x16x32_bf16 v[86:89], v[146:149], v[218:221], v[86:89]
	v_mfma_f32_16x16x32_bf16 v[54:57], v[154:157], v[218:221], v[54:57]
	v_mfma_f32_16x16x32_bf16 v[78:81], v[146:149], v[226:229], v[78:81]
	v_mfma_f32_16x16x32_bf16 v[50:53], v[154:157], v[226:229], v[50:53]
	v_mfma_f32_16x16x32_bf16 v[46:49], v[158:161], v[198:201], v[46:49]
	v_mfma_f32_16x16x32_bf16 v[14:17], v[174:177], v[198:201], v[14:17]
	v_mfma_f32_16x16x32_bf16 v[42:45], v[158:161], v[206:209], v[42:45]
	v_mfma_f32_16x16x32_bf16 v[10:13], v[174:177], v[206:209], v[10:13]
	v_mfma_f32_16x16x32_bf16 v[38:41], v[158:161], v[214:217], v[38:41]
	v_mfma_f32_16x16x32_bf16 v[6:9], v[174:177], v[214:217], v[6:9]
	v_mfma_f32_16x16x32_bf16 v[34:37], v[158:161], v[222:225], v[34:37]
	v_mfma_f32_16x16x32_bf16 v[2:5], v[174:177], v[222:225], v[2:5]
	v_mfma_f32_16x16x32_bf16 v[46:49], v[162:165], v[202:205], v[46:49]
	v_mfma_f32_16x16x32_bf16 v[14:17], v[188:191], v[202:205], v[14:17]
	v_mfma_f32_16x16x32_bf16 v[42:45], v[162:165], v[210:213], v[42:45]
	v_mfma_f32_16x16x32_bf16 v[10:13], v[188:191], v[210:213], v[10:13]
	v_mfma_f32_16x16x32_bf16 v[38:41], v[162:165], v[218:221], v[38:41]
	v_mfma_f32_16x16x32_bf16 v[6:9], v[188:191], v[218:221], v[6:9]
	v_mfma_f32_16x16x32_bf16 v[34:37], v[162:165], v[226:229], v[34:37]
	v_mfma_f32_16x16x32_bf16 v[2:5], v[188:191], v[226:229], v[2:5]
	s_barrier
	s_setprio 0
	s_add_i32 s40, 0, 0x18000
	s_add_i32 s41, 0, 0x1c000
	ds_read_b128 v[142:145], v168 offset:32768
	ds_read_b128 v[146:149], v168 offset:33792
	ds_read_b128 v[150:153], v168 offset:34816
	ds_read_b128 v[154:157], v168 offset:35840
	ds_read_b128 v[158:161], v168 offset:49152
	ds_read_b128 v[162:165], v168 offset:50176
	ds_read_b128 v[174:177], v168 offset:51200
	ds_read_b128 v[188:191], v168 offset:52224
	s_add_u32 s0, s82, 0x80000
	s_addc_u32 s1, s83, 0
	s_mov_b32 m0, s89
	ds_read_b128 v[198:201], v196 offset:32768
	ds_read_b128 v[202:205], v196 offset:33792
	ds_read_b128 v[206:209], v196 offset:34816
	ds_read_b128 v[210:213], v196 offset:35840
	ds_read_b128 v[214:217], v196 offset:36864
	ds_read_b128 v[218:221], v196 offset:37888
	ds_read_b128 v[222:225], v196 offset:38912
	ds_read_b128 v[226:229], v196 offset:39936
	global_load_lds_dwordx4 v130, s[0:1]
	s_mov_b32 m0, s90
	s_nop 0
	global_load_lds_dwordx4 v132, s[0:1]
	s_waitcnt vmcnt(8)
	s_waitcnt lgkmcnt(0)
	s_setprio 1
	s_barrier
; #define PG8_STAGE(bufoff, gbase, voff) do { _Pragma("unroll") for (int _i = 0; _i < 2; ++_i) \
;         __builtin_amdgcn_global_load_lds((const unsigned*)((const char*)(gbase) + (voff)[_i]), (PG8_LAS unsigned*)(lds + (bufoff) + ldsw + _i * 8192), 16, 0, 0); } while (0)
; #define PG8_LDA(dst, b, h) do { _Pragma("unroll") for (int m = 0; m < 4; ++m) _Pragma("unroll") for (int k = 0; k < 2; ++k) dst[m][k] = *(const PG8_LAS bf16x8*)(lds + PG8_SA(b, h) + aoff + m * 2048 + k * 1024); } while (0)
; #define PG8_WAIT_V(n) asm volatile("s_waitcnt vmcnt(" #n ")" ::: "memory")
; #define PG8_WAIT_L(n) asm volatile("s_waitcnt lgkmcnt(" #n ")" ::: "memory")
; #define PG8_BAR __builtin_amdgcn_s_barrier()
; #define PG8_SCHED __builtin_amdgcn_sched_barrier(0)
;     ...
;             PG8_WAIT_V(8); PG8_WAIT_L(0); PG8_BAR; PG8_MMA(0, 0, At, B0); PG8_MMA(0, 1, At, B1); PG8_BAR; PG8_SCHED;
;             PG8_LDA(At, 1, 1); PG8_STAGE(PG8_SB(1, 0), b3, voffB); PG8_STAGE(PG8_SB(1, 1), b3 + hstep, voffB); PG8_STAGE(PG8_SA(1, 0), a3, voffA);
;             PG8_WAIT_V(8); PG8_WAIT_L(0); PG8_BAR; PG8_MMA(1, 0, At, B0); PG8_MMA(1, 1, At, B1); PG8_BAR; PG8_SCHED;
	v_mfma_f32_16x16x32_bf16 v[126:129], v[142:145], v[198:201], v[126:129]
	v_mfma_f32_16x16x32_bf16 v[110:113], v[150:153], v[198:201], v[110:113]
	v_mfma_f32_16x16x32_bf16 v[122:125], v[142:145], v[206:209], v[122:125]
	v_mfma_f32_16x16x32_bf16 v[106:109], v[150:153], v[206:209], v[106:109]
	v_mfma_f32_16x16x32_bf16 v[118:121], v[142:145], v[214:217], v[118:121]
	v_mfma_f32_16x16x32_bf16 v[102:105], v[150:153], v[214:217], v[102:105]
	v_mfma_f32_16x16x32_bf16 v[114:117], v[142:145], v[222:225], v[114:117]
	v_mfma_f32_16x16x32_bf16 v[98:101], v[150:153], v[222:225], v[98:101]
	v_mfma_f32_16x16x32_bf16 v[126:129], v[146:149], v[202:205], v[126:129]
	v_mfma_f32_16x16x32_bf16 v[110:113], v[154:157], v[202:205], v[110:113]
	v_mfma_f32_16x16x32_bf16 v[122:125], v[146:149], v[210:213], v[122:125]
	v_mfma_f32_16x16x32_bf16 v[106:109], v[154:157], v[210:213], v[106:109]
	v_mfma_f32_16x16x32_bf16 v[118:121], v[146:149], v[218:221], v[118:121]
	v_mfma_f32_16x16x32_bf16 v[102:105], v[154:157], v[218:221], v[102:105]
	v_mfma_f32_16x16x32_bf16 v[114:117], v[146:149], v[226:229], v[114:117]
	v_mfma_f32_16x16x32_bf16 v[98:101], v[154:157], v[226:229], v[98:101]
	v_mfma_f32_16x16x32_bf16 v[82:85], v[158:161], v[198:201], v[82:85]
	v_mfma_f32_16x16x32_bf16 v[30:33], v[174:177], v[198:201], v[30:33]
	v_mfma_f32_16x16x32_bf16 v[70:73], v[158:161], v[206:209], v[70:73]
	v_mfma_f32_16x16x32_bf16 v[26:29], v[174:177], v[206:209], v[26:29]
	v_mfma_f32_16x16x32_bf16 v[66:69], v[158:161], v[214:217], v[66:69]
	v_mfma_f32_16x16x32_bf16 v[22:25], v[174:177], v[214:217], v[22:25]
	v_mfma_f32_16x16x32_bf16 v[58:61], v[158:161], v[222:225], v[58:61]
	v_mfma_f32_16x16x32_bf16 v[18:21], v[174:177], v[222:225], v[18:21]
	v_mfma_f32_16x16x32_bf16 v[82:85], v[162:165], v[202:205], v[82:85]
	v_mfma_f32_16x16x32_bf16 v[30:33], v[188:191], v[202:205], v[30:33]
	v_mfma_f32_16x16x32_bf16 v[70:73], v[162:165], v[210:213], v[70:73]
	v_mfma_f32_16x16x32_bf16 v[26:29], v[188:191], v[210:213], v[26:29]
	v_mfma_f32_16x16x32_bf16 v[66:69], v[162:165], v[218:221], v[66:69]
	v_mfma_f32_16x16x32_bf16 v[22:25], v[188:191], v[218:221], v[22:25]
	v_mfma_f32_16x16x32_bf16 v[58:61], v[162:165], v[226:229], v[58:61]
	v_mfma_f32_16x16x32_bf16 v[18:21], v[188:191], v[226:229], v[18:21]
	s_barrier
	s_setprio 0
	s_add_i32 s0, s40, s87
	s_mov_b32 m0, s0
	ds_read_b128 v[198:201], v196 offset:49152
	ds_read_b128 v[202:205], v196 offset:50176
	ds_read_b128 v[206:209], v196 offset:51200
	ds_read_b128 v[210:213], v196 offset:52224
	ds_read_b128 v[214:217], v196 offset:53248
	ds_read_b128 v[218:221], v196 offset:54272
	ds_read_b128 v[222:225], v196 offset:55296
	ds_read_b128 v[226:229], v196 offset:56320
	s_add_u32 s100, s80, 0x80
	s_addc_u32 s101, s81, 0
	global_load_lds_dwordx4 v182, s[100:101]
	s_add_i32 m0, s0, 0x2000
	s_add_u32 s0, s80, 0x80080
	s_addc_u32 s1, s81, 0
	s_add_i32 s40, s41, s87
	global_load_lds_dwordx4 v134, s[100:101]
	s_mov_b32 m0, s40
	s_nop 0
	global_load_lds_dwordx4 v182, s[0:1]
	s_add_i32 m0, s40, 0x2000
	s_nop 0
	global_load_lds_dwordx4 v134, s[0:1]
	s_mov_b32 m0, s94
	s_nop 0
	s_add_u32 s100, s82, 0x80
	s_addc_u32 s101, s83, 0
	global_load_lds_dwordx4 v130, s[100:101]
	s_mov_b32 m0, s95
	s_nop 0
	global_load_lds_dwordx4 v132, s[100:101]
	s_waitcnt vmcnt(8)
	s_waitcnt lgkmcnt(0)
	s_setprio 1
	s_barrier
	v_mfma_f32_16x16x32_bf16 v[94:97], v[142:145], v[198:201], v[94:97]
	v_mfma_f32_16x16x32_bf16 v[74:77], v[150:153], v[198:201], v[74:77]
	v_mfma_f32_16x16x32_bf16 v[90:93], v[142:145], v[206:209], v[90:93]
	v_mfma_f32_16x16x32_bf16 v[62:65], v[150:153], v[206:209], v[62:65]
	v_mfma_f32_16x16x32_bf16 v[86:89], v[142:145], v[214:217], v[86:89]
	v_mfma_f32_16x16x32_bf16 v[54:57], v[150:153], v[214:217], v[54:57]
	v_mfma_f32_16x16x32_bf16 v[78:81], v[142:145], v[222:225], v[78:81]
	v_mfma_f32_16x16x32_bf16 v[50:53], v[150:153], v[222:225], v[50:53]
	v_mfma_f32_16x16x32_bf16 v[94:97], v[146:149], v[202:205], v[94:97]
	v_mfma_f32_16x16x32_bf16 v[74:77], v[154:157], v[202:205], v[74:77]
	v_mfma_f32_16x16x32_bf16 v[90:93], v[146:149], v[210:213], v[90:93]
	v_mfma_f32_16x16x32_bf16 v[62:65], v[154:157], v[210:213], v[62:65]
	v_mfma_f32_16x16x32_bf16 v[86:89], v[146:149], v[218:221], v[86:89]
	v_mfma_f32_16x16x32_bf16 v[54:57], v[154:157], v[218:221], v[54:57]
	v_mfma_f32_16x16x32_bf16 v[78:81], v[146:149], v[226:229], v[78:81]
	v_mfma_f32_16x16x32_bf16 v[50:53], v[154:157], v[226:229], v[50:53]
	v_mfma_f32_16x16x32_bf16 v[46:49], v[158:161], v[198:201], v[46:49]
	v_mfma_f32_16x16x32_bf16 v[14:17], v[174:177], v[198:201], v[14:17]
	v_mfma_f32_16x16x32_bf16 v[42:45], v[158:161], v[206:209], v[42:45]
	v_mfma_f32_16x16x32_bf16 v[10:13], v[174:177], v[206:209], v[10:13]
	v_mfma_f32_16x16x32_bf16 v[38:41], v[158:161], v[214:217], v[38:41]
	v_mfma_f32_16x16x32_bf16 v[6:9], v[174:177], v[214:217], v[6:9]
	v_mfma_f32_16x16x32_bf16 v[34:37], v[158:161], v[222:225], v[34:37]
	v_mfma_f32_16x16x32_bf16 v[2:5], v[174:177], v[222:225], v[2:5]
	v_mfma_f32_16x16x32_bf16 v[46:49], v[162:165], v[202:205], v[46:49]
	v_mfma_f32_16x16x32_bf16 v[14:17], v[188:191], v[202:205], v[14:17]
	v_mfma_f32_16x16x32_bf16 v[42:45], v[162:165], v[210:213], v[42:45]
	v_mfma_f32_16x16x32_bf16 v[10:13], v[188:191], v[210:213], v[10:13]
	v_mfma_f32_16x16x32_bf16 v[38:41], v[162:165], v[218:221], v[38:41]
	v_mfma_f32_16x16x32_bf16 v[6:9], v[188:191], v[218:221], v[6:9]
	v_mfma_f32_16x16x32_bf16 v[34:37], v[162:165], v[226:229], v[34:37]
	v_mfma_f32_16x16x32_bf16 v[2:5], v[188:191], v[226:229], v[2:5]
	s_barrier
	s_setprio 0
	s_add_i32 s37, s37, 2
	s_add_u32 s78, s78, 0x100
	s_addc_u32 s79, s79, 0
	s_add_u32 s33, s33, 0x100
	s_addc_u32 s35, s35, 0
	s_cmp_gt_u32 s37, 29
	s_cbranch_scc0 .LBB0_234
	s_and_b64 vcc, exec, s[64:65]
	s_cbranch_vccz .LBB0_237
	s_barrier

;     __host__ __device__ bool next(int i, Unit& u) const { const long L = (long)i * G + c; if (L >= lim) return false; unit_of((int)L, u); return true; }
;     __device__ __forceinline__ bool next(int i, Unit& v) const { if (i != 0) return false; v = u; return true; }
; #define PG8_STAGE(bufoff, gbase, voff) do { _Pragma("unroll") for (int _i = 0; _i < 2; ++_i) \
;         __builtin_amdgcn_global_load_lds((const unsigned*)((const char*)(gbase) + (voff)[_i]), (PG8_LAS unsigned*)(lds + (bufoff) + ldsw + _i * 8192), 16, 0, 0); } while (0)
; #define PG8_LDA(dst, b, h) do { _Pragma("unroll") for (int m = 0; m < 4; ++m) _Pragma("unroll") for (int k = 0; k < 2; ++k) dst[m][k] = *(const PG8_LAS bf16x8*)(lds + PG8_SA(b, h) + aoff + m * 2048 + k * 1024); } while (0)
; #define PG8_WAIT_L(n) asm volatile("s_waitcnt lgkmcnt(" #n ")" ::: "memory")
;     ...
;         const bool has_next = S.next(ui + 1, nxt);
;         if constexpr (TP == 3) { if (ui > 0) tp_acc += __builtin_amdgcn_s_memrealtime() - tp3; }
;         const char* nA = has_next ? (const char*)g.A + (size_t)nxt.pm * tstep : cA; const char* nB = has_next ? (const char*)g.Bt + (size_t)nxt.pn * tstep : cB;
;         for (int t = 0; t < nt * KREP; t += 2) {
;             const bool last = (t == nt * KREP - 2);
;             const int t1w = KREP > 1 ? ((t + 1) & (nt - 1)) : t + 1, t2w = KREP > 1 ? ((t + 2) & (nt - 1)) : t + 2;
;             const char* a1 = cA + (size_t)t1w * kstep;
;             const char* a2 = last ? nA : cA + (size_t)t2w * kstep; const char* b2 = last ? nB : cB + (size_t)t2w * kstep;
;             const char* a3 = a2 + kstep; const char* b3 = b2 + kstep;
;             if (last && has_next) S.a_ready(nxt);
;             const int relax = __builtin_amdgcn_readfirstlane((MK_RELAXW && t == 0 && ui > 0) ? 1 : 0);
;             if constexpr (SP2) {
;             PG8_LDB(B0, 0, 0); PG8_LDB(B1, 0, 1); PG8_SCHED; PG8_LDA(At, 0, 0); PG8_STAGE(PG8_SA(1, 1), a1 + hstep, voffA);
;             PG8_WAIT_V_SEL(relax);
;             PG8_WAIT_L(0); PG8_BAR; PG8_MMA(0, 0, At, B0); PG8_MMA(0, 1, At, B1); PG8_BAR; PG8_SCHED;
;     ...
; #pragma unroll
;         for (int a = 0; a < 2; ++a)
; #pragma unroll
;             for (int b = 0; b < 2; ++b)
; #pragma unroll
;                 for (int m = 0; m < 4; ++m)
; #pragma unroll
;                     for (int n = 0; n < 2; ++n) acc[a][b][m][n] = (f32x4){0.f, 0.f, 0.f, 0.f};
.LBB0_540:
	s_ashr_i32 s73, s72, 31
	s_lshl_b64 s[0:1], s[72:73], 20
	s_add_u32 s74, s31, s0
	s_addc_u32 s75, s33, s1
	s_and_b64 s[0:1], s[6:7], exec
	s_cselect_b32 s40, s75, s83
	s_cselect_b32 s41, s74, s82
	s_ashr_i32 s71, s70, 31
	s_lshl_b64 s[0:1], s[70:71], 20
	s_add_u32 s76, s35, s0
	s_addc_u32 s77, s37, s1
	s_and_b64 s[0:1], s[6:7], exec
	s_cselect_b32 s57, s77, s85
	s_cselect_b32 s58, s76, s84
	s_add_u32 s82, s82, 0x80080
	s_addc_u32 s83, s83, 0
	s_add_u32 s59, s84, 0x100
	v_mov_b64_e32 v[2:3], 0
	v_mov_b64_e32 v[4:5], 0
	v_mov_b64_e32 v[6:7], 0
	v_mov_b64_e32 v[8:9], 0
	v_mov_b64_e32 v[10:11], 0
	v_mov_b64_e32 v[12:13], 0
	v_mov_b64_e32 v[14:15], 0
	v_mov_b64_e32 v[16:17], 0
	v_mov_b64_e32 v[18:19], 0
	v_mov_b64_e32 v[20:21], 0
	v_mov_b64_e32 v[22:23], 0
	v_mov_b64_e32 v[24:25], 0
	v_mov_b64_e32 v[26:27], 0
	v_mov_b64_e32 v[28:29], 0
	v_mov_b64_e32 v[30:31], 0
	v_mov_b64_e32 v[32:33], 0
	v_mov_b64_e32 v[34:35], 0
	v_mov_b64_e32 v[36:37], 0
	v_mov_b64_e32 v[38:39], 0
	v_mov_b64_e32 v[40:41], 0
	v_mov_b64_e32 v[42:43], 0
	v_mov_b64_e32 v[44:45], 0
	v_mov_b64_e32 v[46:47], 0
	v_mov_b64_e32 v[48:49], 0
	v_mov_b64_e32 v[50:51], 0
	v_mov_b64_e32 v[52:53], 0
	v_mov_b64_e32 v[54:55], 0
	v_mov_b64_e32 v[56:57], 0
	v_mov_b64_e32 v[58:59], 0
	v_mov_b64_e32 v[60:61], 0
	v_mov_b64_e32 v[62:63], 0
	v_mov_b64_e32 v[64:65], 0
	v_mov_b64_e32 v[66:67], 0
	v_mov_b64_e32 v[68:69], 0
	v_mov_b64_e32 v[70:71], 0
	v_mov_b64_e32 v[72:73], 0
	v_mov_b64_e32 v[74:75], 0
	v_mov_b64_e32 v[76:77], 0
	v_mov_b64_e32 v[78:79], 0
	v_mov_b64_e32 v[80:81], 0
	v_mov_b64_e32 v[82:83], 0
	v_mov_b64_e32 v[84:85], 0
	v_mov_b64_e32 v[86:87], 0
	v_mov_b64_e32 v[88:89], 0
	v_mov_b64_e32 v[106:107], 0
	v_mov_b64_e32 v[108:109], 0
	v_mov_b64_e32 v[110:111], 0
	v_mov_b64_e32 v[112:113], 0
	v_mov_b64_e32 v[114:115], 0
	v_mov_b64_e32 v[116:117], 0
	v_mov_b64_e32 v[118:119], 0
	v_mov_b64_e32 v[120:121], 0
	v_mov_b64_e32 v[122:123], 0
	v_mov_b64_e32 v[124:125], 0
	v_mov_b64_e32 v[126:127], 0
	v_mov_b64_e32 v[128:129], 0
	v_mov_b64_e32 v[130:131], 0
	v_mov_b64_e32 v[132:133], 0
	v_mov_b64_e32 v[134:135], 0
	v_mov_b64_e32 v[136:137], 0
	v_mov_b64_e32 v[138:139], 0
	v_mov_b64_e32 v[140:141], 0
	v_mov_b64_e32 v[142:143], 0
	v_mov_b64_e32 v[144:145], 0
	s_addc_u32 s71, s85, 0
	s_mov_b32 s73, -2
	s_waitcnt lgkmcnt(0)
	v_add_u32_e32 v210, 0x10000, v227
.LBB0_541:
	s_add_u32 s0, s82, 0xfff80080
	s_addc_u32 s1, s83, -1
	s_add_i32 s79, 0, 0x10000
	s_cmp_eq_u32 s73, 28
	s_cselect_b32 s87, s40, s1
	s_cselect_b32 s86, s41, s0
	s_cselect_b32 s85, s57, s71
	s_cselect_b32 s84, s58, s59
	s_add_i32 s81, 0, 0x14000
	ds_read_b128 v[90:93], v210
	ds_read_b128 v[94:97], v210 offset:1024
	ds_read_b128 v[98:101], v210 offset:2048
	ds_read_b128 v[102:105], v210 offset:3072
	ds_read_b128 v[146:149], v210 offset:16384
	ds_read_b128 v[150:153], v210 offset:17408
	ds_read_b128 v[154:157], v210 offset:18432
	ds_read_b128 v[158:161], v210 offset:19456
	s_add_i32 m0, s44, 0xc000
	ds_read_b128 v[162:165], v230
	ds_read_b128 v[166:169], v230 offset:1024
	ds_read_b128 v[184:187], v230 offset:2048
	ds_read_b128 v[190:193], v230 offset:3072
	ds_read_b128 v[194:197], v230 offset:4096
	ds_read_b128 v[198:201], v230 offset:5120
	ds_read_b128 v[202:205], v230 offset:6144
	ds_read_b128 v[206:209], v230 offset:7168
	global_load_lds_dwordx4 v180, s[82:83]
	s_add_i32 m0, s44, 0xe000
	s_nop 0
	global_load_lds_dwordx4 v188, s[82:83]
	s_waitcnt vmcnt(8)
	s_waitcnt lgkmcnt(0)
	s_setprio 1
	s_barrier
	v_mfma_f32_16x16x32_bf16 v[142:145], v[90:93], v[162:165], v[142:145]
	v_mfma_f32_16x16x32_bf16 v[138:141], v[98:101], v[162:165], v[138:141]
	v_mfma_f32_16x16x32_bf16 v[126:129], v[90:93], v[184:187], v[126:129]
	v_mfma_f32_16x16x32_bf16 v[122:125], v[98:101], v[184:187], v[122:125]
	v_mfma_f32_16x16x32_bf16 v[110:113], v[90:93], v[194:197], v[110:113]
	v_mfma_f32_16x16x32_bf16 v[106:109], v[98:101], v[194:197], v[106:109]
	v_mfma_f32_16x16x32_bf16 v[78:81], v[90:93], v[202:205], v[78:81]
	v_mfma_f32_16x16x32_bf16 v[74:77], v[98:101], v[202:205], v[74:77]
	v_mfma_f32_16x16x32_bf16 v[142:145], v[94:97], v[166:169], v[142:145]
	v_mfma_f32_16x16x32_bf16 v[138:141], v[102:105], v[166:169], v[138:141]
	v_mfma_f32_16x16x32_bf16 v[126:129], v[94:97], v[190:193], v[126:129]
	v_mfma_f32_16x16x32_bf16 v[122:125], v[102:105], v[190:193], v[122:125]
	v_mfma_f32_16x16x32_bf16 v[110:113], v[94:97], v[198:201], v[110:113]
	v_mfma_f32_16x16x32_bf16 v[106:109], v[102:105], v[198:201], v[106:109]
	v_mfma_f32_16x16x32_bf16 v[78:81], v[94:97], v[206:209], v[78:81]
	v_mfma_f32_16x16x32_bf16 v[74:77], v[102:105], v[206:209], v[74:77]
	v_mfma_f32_16x16x32_bf16 v[134:137], v[146:149], v[162:165], v[134:137]
	v_mfma_f32_16x16x32_bf16 v[130:133], v[154:157], v[162:165], v[130:133]
	v_mfma_f32_16x16x32_bf16 v[118:121], v[146:149], v[184:187], v[118:121]
	v_mfma_f32_16x16x32_bf16 v[114:117], v[154:157], v[184:187], v[114:117]
	v_mfma_f32_16x16x32_bf16 v[86:89], v[146:149], v[194:197], v[86:89]
	v_mfma_f32_16x16x32_bf16 v[82:85], v[154:157], v[194:197], v[82:85]
	v_mfma_f32_16x16x32_bf16 v[70:73], v[146:149], v[202:205], v[70:73]
	v_mfma_f32_16x16x32_bf16 v[66:69], v[154:157], v[202:205], v[66:69]
	v_mfma_f32_16x16x32_bf16 v[134:137], v[150:153], v[166:169], v[134:137]
	v_mfma_f32_16x16x32_bf16 v[130:133], v[158:161], v[166:169], v[130:133]
	v_mfma_f32_16x16x32_bf16 v[118:121], v[150:153], v[190:193], v[118:121]
	v_mfma_f32_16x16x32_bf16 v[114:117], v[158:161], v[190:193], v[114:117]
	v_mfma_f32_16x16x32_bf16 v[86:89], v[150:153], v[198:201], v[86:89]
	v_mfma_f32_16x16x32_bf16 v[82:85], v[158:161], v[198:201], v[82:85]
	v_mfma_f32_16x16x32_bf16 v[70:73], v[150:153], v[206:209], v[70:73]
	v_mfma_f32_16x16x32_bf16 v[66:69], v[158:161], v[206:209], v[66:69]
	s_barrier
; #define PG8_STAGE(bufoff, gbase, voff) do { _Pragma("unroll") for (int _i = 0; _i < 2; ++_i) \
;         __builtin_amdgcn_global_load_lds((const unsigned*)((const char*)(gbase) + (voff)[_i]), (PG8_LAS unsigned*)(lds + (bufoff) + ldsw + _i * 8192), 16, 0, 0); } while (0)
; #define PG8_LDA(dst, b, h) do { _Pragma("unroll") for (int m = 0; m < 4; ++m) _Pragma("unroll") for (int k = 0; k < 2; ++k) dst[m][k] = *(const PG8_LAS bf16x8*)(lds + PG8_SA(b, h) + aoff + m * 2048 + k * 1024); } while (0)
; #define PG8_LDB(dst, b, h) do { _Pragma("unroll") for (int n = 0; n < 2; ++n) _Pragma("unroll") for (int k = 0; k < 2; ++k) dst[n][k] = *(const PG8_LAS bf16x8*)(lds + PG8_SB(b, h) + boff + n * 2048 + k * 1024); } while (0)
; #define PG8_WAIT_V(n) asm volatile("s_waitcnt vmcnt(" #n ")" ::: "memory")
; #define PG8_WAIT_L(n) asm volatile("s_waitcnt lgkmcnt(" #n ")" ::: "memory")
; #define PG8_WAIT_V_SEL(sel) asm volatile("s_cmp_eq_u32 %0, 0\n\ts_cbranch_scc1 .Lw8_%=\n\ts_waitcnt vmcnt(22)\n\ts_branch .Lwd_%=\n.Lw8_%=:\n\ts_waitcnt vmcnt(8)\n.Lwd_%=:" :: "s"(sel) : "memory", "scc")
; #define PG8_BAR __builtin_amdgcn_s_barrier()
; #define PG8_SCHED __builtin_amdgcn_sched_barrier(0)
;     ...
;             PG8_LDA(At, 0, 1); PG8_STAGE(PG8_SB(0, 0), b2, voffB); PG8_STAGE(PG8_SB(0, 1), b2 + hstep, voffB); PG8_STAGE(PG8_SA(0, 0), a2, voffA);
;             PG8_WAIT_V_SEL(relax);
;             PG8_WAIT_L(0); PG8_BAR; PG8_MMA(1, 0, At, B0); PG8_MMA(1, 1, At, B1); PG8_BAR; PG8_SCHED;
;             PG8_LDB(B0, 1, 0); PG8_LDB(B1, 1, 1); PG8_SCHED; PG8_LDA(At, 1, 0); PG8_STAGE(PG8_SA(0, 1), a2 + hstep, voffA);
;             PG8_WAIT_V(8); PG8_WAIT_L(0); PG8_BAR; PG8_MMA(0, 0, At, B0); PG8_MMA(0, 1, At, B1); PG8_BAR; PG8_SCHED;
	s_setprio 0
	s_add_i32 s0, s79, s30
	s_mov_b32 m0, s0
	ds_read_b128 v[162:165], v230 offset:16384
	ds_read_b128 v[166:169], v230 offset:17408
	ds_read_b128 v[184:187], v230 offset:18432
	ds_read_b128 v[190:193], v230 offset:19456
	ds_read_b128 v[194:197], v230 offset:20480
	ds_read_b128 v[198:201], v230 offset:21504
	ds_read_b128 v[202:205], v230 offset:22528
	ds_read_b128 v[206:209], v230 offset:23552
	global_load_lds_dwordx4 v182, s[84:85]
	s_add_i32 m0, s0, 0x2000
	s_add_u32 s0, s84, 0x80000
	s_addc_u32 s1, s85, 0
	s_add_i32 s79, s81, s30
	global_load_lds_dwordx4 v178, s[84:85]
	s_mov_b32 m0, s79
	s_nop 0
	global_load_lds_dwordx4 v182, s[0:1]
	s_add_i32 m0, s79, 0x2000
	s_nop 0
	global_load_lds_dwordx4 v178, s[0:1]
	s_mov_b32 m0, s44
	s_nop 0
	global_load_lds_dwordx4 v174, s[86:87]
	s_mov_b32 m0, s45
	s_nop 0
	global_load_lds_dwordx4 v176, s[86:87]
	s_waitcnt vmcnt(8)
	s_waitcnt lgkmcnt(0)
	s_setprio 1
	s_barrier
	v_mfma_f32_16x16x32_bf16 v[62:65], v[90:93], v[162:165], v[62:65]
	v_mfma_f32_16x16x32_bf16 v[58:61], v[98:101], v[162:165], v[58:61]
	v_mfma_f32_16x16x32_bf16 v[46:49], v[90:93], v[184:187], v[46:49]
	v_mfma_f32_16x16x32_bf16 v[42:45], v[98:101], v[184:187], v[42:45]
	v_mfma_f32_16x16x32_bf16 v[30:33], v[90:93], v[194:197], v[30:33]
	v_mfma_f32_16x16x32_bf16 v[26:29], v[98:101], v[194:197], v[26:29]
	v_mfma_f32_16x16x32_bf16 v[14:17], v[90:93], v[202:205], v[14:17]
	v_mfma_f32_16x16x32_bf16 v[10:13], v[98:101], v[202:205], v[10:13]
	v_mfma_f32_16x16x32_bf16 v[62:65], v[94:97], v[166:169], v[62:65]
	v_mfma_f32_16x16x32_bf16 v[58:61], v[102:105], v[166:169], v[58:61]
	v_mfma_f32_16x16x32_bf16 v[46:49], v[94:97], v[190:193], v[46:49]
	v_mfma_f32_16x16x32_bf16 v[42:45], v[102:105], v[190:193], v[42:45]
	v_mfma_f32_16x16x32_bf16 v[30:33], v[94:97], v[198:201], v[30:33]
	v_mfma_f32_16x16x32_bf16 v[26:29], v[102:105], v[198:201], v[26:29]
	v_mfma_f32_16x16x32_bf16 v[14:17], v[94:97], v[206:209], v[14:17]
	v_mfma_f32_16x16x32_bf16 v[10:13], v[102:105], v[206:209], v[10:13]
	v_mfma_f32_16x16x32_bf16 v[54:57], v[146:149], v[162:165], v[54:57]
	v_mfma_f32_16x16x32_bf16 v[50:53], v[154:157], v[162:165], v[50:53]
	v_mfma_f32_16x16x32_bf16 v[38:41], v[146:149], v[184:187], v[38:41]
	v_mfma_f32_16x16x32_bf16 v[34:37], v[154:157], v[184:187], v[34:37]
	v_mfma_f32_16x16x32_bf16 v[22:25], v[146:149], v[194:197], v[22:25]
	v_mfma_f32_16x16x32_bf16 v[18:21], v[154:157], v[194:197], v[18:21]
	v_mfma_f32_16x16x32_bf16 v[6:9], v[146:149], v[202:205], v[6:9]
	v_mfma_f32_16x16x32_bf16 v[2:5], v[154:157], v[202:205], v[2:5]
	v_mfma_f32_16x16x32_bf16 v[54:57], v[150:153], v[166:169], v[54:57]
	v_mfma_f32_16x16x32_bf16 v[50:53], v[158:161], v[166:169], v[50:53]
	v_mfma_f32_16x16x32_bf16 v[38:41], v[150:153], v[190:193], v[38:41]
	v_mfma_f32_16x16x32_bf16 v[34:37], v[158:161], v[190:193], v[34:37]
	v_mfma_f32_16x16x32_bf16 v[22:25], v[150:153], v[198:201], v[22:25]
	v_mfma_f32_16x16x32_bf16 v[18:21], v[158:161], v[198:201], v[18:21]
	v_mfma_f32_16x16x32_bf16 v[6:9], v[150:153], v[206:209], v[6:9]
	v_mfma_f32_16x16x32_bf16 v[2:5], v[158:161], v[206:209], v[2:5]
	s_barrier
	s_setprio 0
	s_add_i32 s79, 0, 0x18000
	s_add_i32 s81, 0, 0x1c000
	ds_read_b128 v[90:93], v210 offset:32768
	ds_read_b128 v[94:97], v210 offset:33792
	ds_read_b128 v[98:101], v210 offset:34816
	ds_read_b128 v[102:105], v210 offset:35840
	ds_read_b128 v[146:149], v210 offset:49152
	ds_read_b128 v[150:153], v210 offset:50176
	ds_read_b128 v[154:157], v210 offset:51200
	ds_read_b128 v[158:161], v210 offset:52224
	s_add_u32 s0, s86, 0x80000
	s_addc_u32 s1, s87, 0
	s_mov_b32 m0, s46
	ds_read_b128 v[162:165], v230 offset:32768
	ds_read_b128 v[166:169], v230 offset:33792
	ds_read_b128 v[184:187], v230 offset:34816
	ds_read_b128 v[190:193], v230 offset:35840
	ds_read_b128 v[194:197], v230 offset:36864
	ds_read_b128 v[198:201], v230 offset:37888
	ds_read_b128 v[202:205], v230 offset:38912
	ds_read_b128 v[206:209], v230 offset:39936
	global_load_lds_dwordx4 v174, s[0:1]
	s_mov_b32 m0, s47
	s_nop 0
	global_load_lds_dwordx4 v176, s[0:1]
	s_waitcnt vmcnt(8)
	s_waitcnt lgkmcnt(0)
	s_setprio 1
	s_barrier
; #define PG8_STAGE(bufoff, gbase, voff) do { _Pragma("unroll") for (int _i = 0; _i < 2; ++_i) \
;         __builtin_amdgcn_global_load_lds((const unsigned*)((const char*)(gbase) + (voff)[_i]), (PG8_LAS unsigned*)(lds + (bufoff) + ldsw + _i * 8192), 16, 0, 0); } while (0)
; #define PG8_LDA(dst, b, h) do { _Pragma("unroll") for (int m = 0; m < 4; ++m) _Pragma("unroll") for (int k = 0; k < 2; ++k) dst[m][k] = *(const PG8_LAS bf16x8*)(lds + PG8_SA(b, h) + aoff + m * 2048 + k * 1024); } while (0)
; #define PG8_WAIT_V(n) asm volatile("s_waitcnt vmcnt(" #n ")" ::: "memory")
; #define PG8_WAIT_L(n) asm volatile("s_waitcnt lgkmcnt(" #n ")" ::: "memory")
; #define PG8_BAR __builtin_amdgcn_s_barrier()
; #define PG8_SCHED __builtin_amdgcn_sched_barrier(0)
;     ...
;             PG8_WAIT_V(8); PG8_WAIT_L(0); PG8_BAR; PG8_MMA(0, 0, At, B0); PG8_MMA(0, 1, At, B1); PG8_BAR; PG8_SCHED;
;             PG8_LDA(At, 1, 1); PG8_STAGE(PG8_SB(1, 0), b3, voffB); PG8_STAGE(PG8_SB(1, 1), b3 + hstep, voffB); PG8_STAGE(PG8_SA(1, 0), a3, voffA);
;             PG8_WAIT_V(8); PG8_WAIT_L(0); PG8_BAR; PG8_MMA(1, 0, At, B0); PG8_MMA(1, 1, At, B1); PG8_BAR; PG8_SCHED;
	v_mfma_f32_16x16x32_bf16 v[142:145], v[90:93], v[162:165], v[142:145]
	v_mfma_f32_16x16x32_bf16 v[138:141], v[98:101], v[162:165], v[138:141]
	v_mfma_f32_16x16x32_bf16 v[126:129], v[90:93], v[184:187], v[126:129]
	v_mfma_f32_16x16x32_bf16 v[122:125], v[98:101], v[184:187], v[122:125]
	v_mfma_f32_16x16x32_bf16 v[110:113], v[90:93], v[194:197], v[110:113]
	v_mfma_f32_16x16x32_bf16 v[106:109], v[98:101], v[194:197], v[106:109]
	v_mfma_f32_16x16x32_bf16 v[78:81], v[90:93], v[202:205], v[78:81]
	v_mfma_f32_16x16x32_bf16 v[74:77], v[98:101], v[202:205], v[74:77]
	v_mfma_f32_16x16x32_bf16 v[142:145], v[94:97], v[166:169], v[142:145]
	v_mfma_f32_16x16x32_bf16 v[138:141], v[102:105], v[166:169], v[138:141]
	v_mfma_f32_16x16x32_bf16 v[126:129], v[94:97], v[190:193], v[126:129]
	v_mfma_f32_16x16x32_bf16 v[122:125], v[102:105], v[190:193], v[122:125]
	v_mfma_f32_16x16x32_bf16 v[110:113], v[94:97], v[198:201], v[110:113]
	v_mfma_f32_16x16x32_bf16 v[106:109], v[102:105], v[198:201], v[106:109]
	v_mfma_f32_16x16x32_bf16 v[78:81], v[94:97], v[206:209], v[78:81]
	v_mfma_f32_16x16x32_bf16 v[74:77], v[102:105], v[206:209], v[74:77]
	v_mfma_f32_16x16x32_bf16 v[134:137], v[146:149], v[162:165], v[134:137]
	v_mfma_f32_16x16x32_bf16 v[130:133], v[154:157], v[162:165], v[130:133]
	v_mfma_f32_16x16x32_bf16 v[118:121], v[146:149], v[184:187], v[118:121]
	v_mfma_f32_16x16x32_bf16 v[114:117], v[154:157], v[184:187], v[114:117]
	v_mfma_f32_16x16x32_bf16 v[86:89], v[146:149], v[194:197], v[86:89]
	v_mfma_f32_16x16x32_bf16 v[82:85], v[154:157], v[194:197], v[82:85]
	v_mfma_f32_16x16x32_bf16 v[70:73], v[146:149], v[202:205], v[70:73]
	v_mfma_f32_16x16x32_bf16 v[66:69], v[154:157], v[202:205], v[66:69]
	v_mfma_f32_16x16x32_bf16 v[134:137], v[150:153], v[166:169], v[134:137]
	v_mfma_f32_16x16x32_bf16 v[130:133], v[158:161], v[166:169], v[130:133]
	v_mfma_f32_16x16x32_bf16 v[118:121], v[150:153], v[190:193], v[118:121]
	v_mfma_f32_16x16x32_bf16 v[114:117], v[158:161], v[190:193], v[114:117]
	v_mfma_f32_16x16x32_bf16 v[86:89], v[150:153], v[198:201], v[86:89]
	v_mfma_f32_16x16x32_bf16 v[82:85], v[158:161], v[198:201], v[82:85]
	v_mfma_f32_16x16x32_bf16 v[70:73], v[150:153], v[206:209], v[70:73]
	v_mfma_f32_16x16x32_bf16 v[66:69], v[158:161], v[206:209], v[66:69]
	s_barrier
	s_setprio 0
	s_add_i32 s0, s79, s30
	s_mov_b32 m0, s0
	ds_read_b128 v[162:165], v230 offset:49152
	ds_read_b128 v[166:169], v230 offset:50176
	ds_read_b128 v[184:187], v230 offset:51200
	ds_read_b128 v[190:193], v230 offset:52224
	ds_read_b128 v[194:197], v230 offset:53248
	ds_read_b128 v[198:201], v230 offset:54272
	ds_read_b128 v[202:205], v230 offset:55296
	ds_read_b128 v[206:209], v230 offset:56320
	s_add_u32 s100, s84, 0x80
	s_addc_u32 s101, s85, 0
	global_load_lds_dwordx4 v182, s[100:101]
	s_add_i32 m0, s0, 0x2000
	s_add_u32 s0, s84, 0x80080
	s_addc_u32 s1, s85, 0
	s_add_i32 s79, s81, s30
	global_load_lds_dwordx4 v178, s[100:101]
	s_mov_b32 m0, s79
	s_nop 0
	global_load_lds_dwordx4 v182, s[0:1]
	s_add_i32 m0, s79, 0x2000
	s_nop 0
	global_load_lds_dwordx4 v178, s[0:1]
	s_mov_b32 m0, s49
	s_nop 0
	s_add_u32 s100, s86, 0x80
	s_addc_u32 s101, s87, 0
	global_load_lds_dwordx4 v174, s[100:101]
	s_mov_b32 m0, s50
	s_nop 0
	global_load_lds_dwordx4 v176, s[100:101]
	s_waitcnt vmcnt(8)
	s_waitcnt lgkmcnt(0)
	s_setprio 1
	s_barrier
	v_mfma_f32_16x16x32_bf16 v[62:65], v[90:93], v[162:165], v[62:65]
	v_mfma_f32_16x16x32_bf16 v[58:61], v[98:101], v[162:165], v[58:61]
	v_mfma_f32_16x16x32_bf16 v[46:49], v[90:93], v[184:187], v[46:49]
	v_mfma_f32_16x16x32_bf16 v[42:45], v[98:101], v[184:187], v[42:45]
	v_mfma_f32_16x16x32_bf16 v[30:33], v[90:93], v[194:197], v[30:33]
	v_mfma_f32_16x16x32_bf16 v[26:29], v[98:101], v[194:197], v[26:29]
	v_mfma_f32_16x16x32_bf16 v[14:17], v[90:93], v[202:205], v[14:17]
	v_mfma_f32_16x16x32_bf16 v[10:13], v[98:101], v[202:205], v[10:13]
	v_mfma_f32_16x16x32_bf16 v[62:65], v[94:97], v[166:169], v[62:65]
	v_mfma_f32_16x16x32_bf16 v[58:61], v[102:105], v[166:169], v[58:61]
	v_mfma_f32_16x16x32_bf16 v[46:49], v[94:97], v[190:193], v[46:49]
	v_mfma_f32_16x16x32_bf16 v[42:45], v[102:105], v[190:193], v[42:45]
	v_mfma_f32_16x16x32_bf16 v[30:33], v[94:97], v[198:201], v[30:33]
	v_mfma_f32_16x16x32_bf16 v[26:29], v[102:105], v[198:201], v[26:29]
	v_mfma_f32_16x16x32_bf16 v[14:17], v[94:97], v[206:209], v[14:17]
	v_mfma_f32_16x16x32_bf16 v[10:13], v[102:105], v[206:209], v[10:13]
	v_mfma_f32_16x16x32_bf16 v[54:57], v[146:149], v[162:165], v[54:57]
	v_mfma_f32_16x16x32_bf16 v[50:53], v[154:157], v[162:165], v[50:53]
	v_mfma_f32_16x16x32_bf16 v[38:41], v[146:149], v[184:187], v[38:41]
	v_mfma_f32_16x16x32_bf16 v[34:37], v[154:157], v[184:187], v[34:37]
	v_mfma_f32_16x16x32_bf16 v[22:25], v[146:149], v[194:197], v[22:25]
	v_mfma_f32_16x16x32_bf16 v[18:21], v[154:157], v[194:197], v[18:21]
	v_mfma_f32_16x16x32_bf16 v[6:9], v[146:149], v[202:205], v[6:9]
	v_mfma_f32_16x16x32_bf16 v[2:5], v[154:157], v[202:205], v[2:5]
	v_mfma_f32_16x16x32_bf16 v[54:57], v[150:153], v[166:169], v[54:57]
	v_mfma_f32_16x16x32_bf16 v[50:53], v[158:161], v[166:169], v[50:53]
	v_mfma_f32_16x16x32_bf16 v[38:41], v[150:153], v[190:193], v[38:41]
	v_mfma_f32_16x16x32_bf16 v[34:37], v[158:161], v[190:193], v[34:37]
	v_mfma_f32_16x16x32_bf16 v[22:25], v[150:153], v[198:201], v[22:25]
	v_mfma_f32_16x16x32_bf16 v[18:21], v[158:161], v[198:201], v[18:21]
	v_mfma_f32_16x16x32_bf16 v[6:9], v[150:153], v[206:209], v[6:9]
	v_mfma_f32_16x16x32_bf16 v[2:5], v[158:161], v[206:209], v[2:5]
	s_barrier
	s_setprio 0
	s_add_i32 s73, s73, 2
	s_add_u32 s82, s82, 0x100
	s_addc_u32 s83, s83, 0
	s_add_u32 s59, s59, 0x100
	s_addc_u32 s71, s71, 0
	s_cmp_gt_u32 s73, 29
	s_cbranch_scc0 .LBB0_541
	s_and_b64 vcc, exec, s[68:69]
	s_cbranch_vccz .LBB0_544
	s_barrier

;     __host__ __device__ bool next(int i, Unit& u) const { const long L = (long)i * G + c; if (L >= lim) return false; unit_of((int)L, u); return true; }
;     __device__ __forceinline__ bool next(int i, Unit& v) const { if (i != 0) return false; v = u; return true; }
; #define PG8_STAGE(bufoff, gbase, voff) do { _Pragma("unroll") for (int _i = 0; _i < 2; ++_i) \
;         __builtin_amdgcn_global_load_lds((const unsigned*)((const char*)(gbase) + (voff)[_i]), (PG8_LAS unsigned*)(lds + (bufoff) + ldsw + _i * 8192), 16, 0, 0); } while (0)
; #define PG8_LDA(dst, b, h) do { _Pragma("unroll") for (int m = 0; m < 4; ++m) _Pragma("unroll") for (int k = 0; k < 2; ++k) dst[m][k] = *(const PG8_LAS bf16x8*)(lds + PG8_SA(b, h) + aoff + m * 2048 + k * 1024); } while (0)
;     ...
;         const bool has_next = S.next(ui + 1, nxt);
;         if constexpr (TP == 3) { if (ui > 0) tp_acc += __builtin_amdgcn_s_memrealtime() - tp3; }
;         const char* nA = has_next ? (const char*)g.A + (size_t)nxt.pm * tstep : cA; const char* nB = has_next ? (const char*)g.Bt + (size_t)nxt.pn * tstep : cB;
;         for (int t = 0; t < nt * KREP; t += 2) {
;             const bool last = (t == nt * KREP - 2);
;             const int t1w = KREP > 1 ? ((t + 1) & (nt - 1)) : t + 1, t2w = KREP > 1 ? ((t + 2) & (nt - 1)) : t + 2;
;             const char* a1 = cA + (size_t)t1w * kstep;
;             const char* a2 = last ? nA : cA + (size_t)t2w * kstep; const char* b2 = last ? nB : cB + (size_t)t2w * kstep;
;             const char* a3 = a2 + kstep; const char* b3 = b2 + kstep;
;             if (last && has_next) S.a_ready(nxt);
;             const int relax = __builtin_amdgcn_readfirstlane((MK_RELAXW && t == 0 && ui > 0) ? 1 : 0);
;             if constexpr (SP2) {
;             PG8_LDB(B0, 0, 0); PG8_LDB(B1, 0, 1); PG8_SCHED; PG8_LDA(At, 0, 0); PG8_STAGE(PG8_SA(1, 1), a1 + hstep, voffA);
;             PG8_WAIT_V_SEL(relax);
;             PG8_WAIT_L(0); PG8_BAR; PG8_MMA(0, 0, At, B0); PG8_MMA(0, 1, At, B1); PG8_BAR; PG8_SCHED;
;     ...
; #pragma unroll
;         for (int a = 0; a < 2; ++a)
; #pragma unroll
;             for (int b = 0; b < 2; ++b)
; #pragma unroll
;                 for (int m = 0; m < 4; ++m)
; #pragma unroll
;                     for (int n = 0; n < 2; ++n) acc[a][b][m][n] = (f32x4){0.f, 0.f, 0.f, 0.f};
;         cur = nxt; cA = nA; cB = nB; ++ui;
.LBB0_595:
	s_ashr_i32 s67, s66, 31
	s_lshl_b64 s[0:1], s[66:67], 20
	s_add_u32 s68, s31, s0
	s_addc_u32 s69, s33, s1
	s_and_b64 s[0:1], s[2:3], exec
	s_cselect_b32 s40, s69, s75
	s_cselect_b32 s41, s68, s74
	s_ashr_i32 s65, s64, 31
	s_lshl_b64 s[0:1], s[64:65], 20
	s_add_u32 s70, s24, s0
	s_addc_u32 s71, s30, s1
	s_and_b64 s[0:1], s[2:3], exec
	s_cselect_b32 s65, s71, s77
	s_cselect_b32 s73, s70, s76
	s_add_u32 s74, s74, 0x80080
	s_addc_u32 s75, s75, 0
	s_add_u32 s80, s76, 0x100
	v_mov_b64_e32 v[2:3], 0
	v_mov_b64_e32 v[4:5], 0
	v_mov_b64_e32 v[6:7], 0
	v_mov_b64_e32 v[8:9], 0
	v_mov_b64_e32 v[10:11], 0
	v_mov_b64_e32 v[12:13], 0
	v_mov_b64_e32 v[14:15], 0
	v_mov_b64_e32 v[16:17], 0
	v_mov_b64_e32 v[18:19], 0
	v_mov_b64_e32 v[20:21], 0
	v_mov_b64_e32 v[22:23], 0
	v_mov_b64_e32 v[24:25], 0
	v_mov_b64_e32 v[26:27], 0
	v_mov_b64_e32 v[28:29], 0
	v_mov_b64_e32 v[30:31], 0
	v_mov_b64_e32 v[32:33], 0
	v_mov_b64_e32 v[34:35], 0
	v_mov_b64_e32 v[36:37], 0
	v_mov_b64_e32 v[38:39], 0
	v_mov_b64_e32 v[40:41], 0
	v_mov_b64_e32 v[42:43], 0
	v_mov_b64_e32 v[44:45], 0
	v_mov_b64_e32 v[46:47], 0
	v_mov_b64_e32 v[48:49], 0
	v_mov_b64_e32 v[50:51], 0
	v_mov_b64_e32 v[52:53], 0
	v_mov_b64_e32 v[54:55], 0
	v_mov_b64_e32 v[56:57], 0
	v_mov_b64_e32 v[58:59], 0
	v_mov_b64_e32 v[60:61], 0
	v_mov_b64_e32 v[62:63], 0
	v_mov_b64_e32 v[64:65], 0
	v_mov_b64_e32 v[66:67], 0
	v_mov_b64_e32 v[68:69], 0
	v_mov_b64_e32 v[70:71], 0
	v_mov_b64_e32 v[72:73], 0
	v_mov_b64_e32 v[74:75], 0
	v_mov_b64_e32 v[76:77], 0
	v_mov_b64_e32 v[78:79], 0
	v_mov_b64_e32 v[80:81], 0
	v_mov_b64_e32 v[82:83], 0
	v_mov_b64_e32 v[84:85], 0
	v_mov_b64_e32 v[86:87], 0
	v_mov_b64_e32 v[88:89], 0
	v_mov_b64_e32 v[90:91], 0
	v_mov_b64_e32 v[92:93], 0
	v_mov_b64_e32 v[94:95], 0
	v_mov_b64_e32 v[96:97], 0
	v_mov_b64_e32 v[98:99], 0
	v_mov_b64_e32 v[100:101], 0
	v_mov_b64_e32 v[102:103], 0
	v_mov_b64_e32 v[104:105], 0
	v_mov_b64_e32 v[106:107], 0
	v_mov_b64_e32 v[108:109], 0
	v_mov_b64_e32 v[110:111], 0
	v_mov_b64_e32 v[112:113], 0
	v_mov_b64_e32 v[114:115], 0
	v_mov_b64_e32 v[116:117], 0
	v_mov_b64_e32 v[118:119], 0
	v_mov_b64_e32 v[120:121], 0
	v_mov_b64_e32 v[122:123], 0
	v_mov_b64_e32 v[124:125], 0
	v_mov_b64_e32 v[126:127], 0
	v_mov_b64_e32 v[128:129], 0
	s_addc_u32 s81, s77, 0
	s_mov_b32 s82, -2
	v_add_u32_e32 v180, 0x10000, v146
.LBB0_596:
	s_add_u32 s0, s74, 0xfff80080
	s_addc_u32 s1, s75, -1
	s_add_i32 s83, 0, 0x10000
	s_cmp_eq_u32 s82, 28
	s_cselect_b32 s79, s40, s1
	s_cselect_b32 s78, s41, s0
	s_cselect_b32 s77, s65, s81
	s_cselect_b32 s76, s73, s80
	s_add_i32 s84, 0, 0x14000
	ds_read_b128 v[150:153], v180
	ds_read_b128 v[154:157], v180 offset:1024
	ds_read_b128 v[158:161], v180 offset:2048
	ds_read_b128 v[162:165], v180 offset:3072
	ds_read_b128 v[166:169], v180 offset:16384
	ds_read_b128 v[172:175], v180 offset:17408
	ds_read_b128 v[176:179], v180 offset:18432
	ds_read_b128 v[188:191], v180 offset:19456
	s_add_i32 m0, s35, 0xc000
	ds_read_b128 v[192:195], v148
	ds_read_b128 v[196:199], v148 offset:1024
	ds_read_b128 v[200:203], v148 offset:2048
	ds_read_b128 v[204:207], v148 offset:3072
	ds_read_b128 v[208:211], v148 offset:4096
	ds_read_b128 v[212:215], v148 offset:5120
	ds_read_b128 v[216:219], v148 offset:6144
	ds_read_b128 v[220:223], v148 offset:7168
	global_load_lds_dwordx4 v140, s[74:75]
	s_add_i32 m0, s35, 0xe000
	s_nop 0
	global_load_lds_dwordx4 v142, s[74:75]
	s_waitcnt vmcnt(8)
	s_waitcnt lgkmcnt(0)
	s_setprio 1
	s_barrier
	v_mfma_f32_16x16x32_bf16 v[126:129], v[150:153], v[192:195], v[126:129]
	v_mfma_f32_16x16x32_bf16 v[110:113], v[158:161], v[192:195], v[110:113]
	v_mfma_f32_16x16x32_bf16 v[122:125], v[150:153], v[200:203], v[122:125]
	v_mfma_f32_16x16x32_bf16 v[106:109], v[158:161], v[200:203], v[106:109]
	v_mfma_f32_16x16x32_bf16 v[118:121], v[150:153], v[208:211], v[118:121]
	v_mfma_f32_16x16x32_bf16 v[102:105], v[158:161], v[208:211], v[102:105]
	v_mfma_f32_16x16x32_bf16 v[114:117], v[150:153], v[216:219], v[114:117]
	v_mfma_f32_16x16x32_bf16 v[98:101], v[158:161], v[216:219], v[98:101]
	v_mfma_f32_16x16x32_bf16 v[126:129], v[154:157], v[196:199], v[126:129]
	v_mfma_f32_16x16x32_bf16 v[110:113], v[162:165], v[196:199], v[110:113]
	v_mfma_f32_16x16x32_bf16 v[122:125], v[154:157], v[204:207], v[122:125]
	v_mfma_f32_16x16x32_bf16 v[106:109], v[162:165], v[204:207], v[106:109]
	v_mfma_f32_16x16x32_bf16 v[118:121], v[154:157], v[212:215], v[118:121]
	v_mfma_f32_16x16x32_bf16 v[102:105], v[162:165], v[212:215], v[102:105]
	v_mfma_f32_16x16x32_bf16 v[114:117], v[154:157], v[220:223], v[114:117]
	v_mfma_f32_16x16x32_bf16 v[98:101], v[162:165], v[220:223], v[98:101]
	v_mfma_f32_16x16x32_bf16 v[70:73], v[166:169], v[192:195], v[70:73]
	v_mfma_f32_16x16x32_bf16 v[50:53], v[176:179], v[192:195], v[50:53]
	v_mfma_f32_16x16x32_bf16 v[66:69], v[166:169], v[200:203], v[66:69]
	v_mfma_f32_16x16x32_bf16 v[42:45], v[176:179], v[200:203], v[42:45]
	v_mfma_f32_16x16x32_bf16 v[58:61], v[166:169], v[208:211], v[58:61]
	v_mfma_f32_16x16x32_bf16 v[38:41], v[176:179], v[208:211], v[38:41]
	v_mfma_f32_16x16x32_bf16 v[46:49], v[166:169], v[216:219], v[46:49]
	v_mfma_f32_16x16x32_bf16 v[34:37], v[176:179], v[216:219], v[34:37]
	v_mfma_f32_16x16x32_bf16 v[70:73], v[172:175], v[196:199], v[70:73]
	v_mfma_f32_16x16x32_bf16 v[50:53], v[188:191], v[196:199], v[50:53]
	v_mfma_f32_16x16x32_bf16 v[66:69], v[172:175], v[204:207], v[66:69]
	v_mfma_f32_16x16x32_bf16 v[42:45], v[188:191], v[204:207], v[42:45]
	v_mfma_f32_16x16x32_bf16 v[58:61], v[172:175], v[212:215], v[58:61]
	v_mfma_f32_16x16x32_bf16 v[38:41], v[188:191], v[212:215], v[38:41]
	v_mfma_f32_16x16x32_bf16 v[46:49], v[172:175], v[220:223], v[46:49]
	v_mfma_f32_16x16x32_bf16 v[34:37], v[188:191], v[220:223], v[34:37]
	s_barrier
; #define PG8_STAGE(bufoff, gbase, voff) do { _Pragma("unroll") for (int _i = 0; _i < 2; ++_i) \
;         __builtin_amdgcn_global_load_lds((const unsigned*)((const char*)(gbase) + (voff)[_i]), (PG8_LAS unsigned*)(lds + (bufoff) + ldsw + _i * 8192), 16, 0, 0); } while (0)
; #define PG8_LDA(dst, b, h) do { _Pragma("unroll") for (int m = 0; m < 4; ++m) _Pragma("unroll") for (int k = 0; k < 2; ++k) dst[m][k] = *(const PG8_LAS bf16x8*)(lds + PG8_SA(b, h) + aoff + m * 2048 + k * 1024); } while (0)
; #define PG8_LDB(dst, b, h) do { _Pragma("unroll") for (int n = 0; n < 2; ++n) _Pragma("unroll") for (int k = 0; k < 2; ++k) dst[n][k] = *(const PG8_LAS bf16x8*)(lds + PG8_SB(b, h) + boff + n * 2048 + k * 1024); } while (0)
; #define PG8_WAIT_V(n) asm volatile("s_waitcnt vmcnt(" #n ")" ::: "memory")
; #define PG8_WAIT_L(n) asm volatile("s_waitcnt lgkmcnt(" #n ")" ::: "memory")
; #define PG8_WAIT_V_SEL(sel) asm volatile("s_cmp_eq_u32 %0, 0\n\ts_cbranch_scc1 .Lw8_%=\n\ts_waitcnt vmcnt(22)\n\ts_branch .Lwd_%=\n.Lw8_%=:\n\ts_waitcnt vmcnt(8)\n.Lwd_%=:" :: "s"(sel) : "memory", "scc")
; #define PG8_BAR __builtin_amdgcn_s_barrier()
; #define PG8_SCHED __builtin_amdgcn_sched_barrier(0)
;     ...
;             PG8_LDA(At, 0, 1); PG8_STAGE(PG8_SB(0, 0), b2, voffB); PG8_STAGE(PG8_SB(0, 1), b2 + hstep, voffB); PG8_STAGE(PG8_SA(0, 0), a2, voffA);
;             PG8_WAIT_V_SEL(relax);
;             PG8_WAIT_L(0); PG8_BAR; PG8_MMA(1, 0, At, B0); PG8_MMA(1, 1, At, B1); PG8_BAR; PG8_SCHED;
;             PG8_LDB(B0, 1, 0); PG8_LDB(B1, 1, 1); PG8_SCHED; PG8_LDA(At, 1, 0); PG8_STAGE(PG8_SA(0, 1), a2 + hstep, voffA);
;             PG8_WAIT_V(8); PG8_WAIT_L(0); PG8_BAR; PG8_MMA(0, 0, At, B0); PG8_MMA(0, 1, At, B1); PG8_BAR; PG8_SCHED;
	s_setprio 0
	s_add_i32 s0, s83, s20
	s_mov_b32 m0, s0
	ds_read_b128 v[192:195], v148 offset:16384
	ds_read_b128 v[196:199], v148 offset:17408
	ds_read_b128 v[200:203], v148 offset:18432
	ds_read_b128 v[204:207], v148 offset:19456
	ds_read_b128 v[208:211], v148 offset:20480
	ds_read_b128 v[212:215], v148 offset:21504
	ds_read_b128 v[216:219], v148 offset:22528
	ds_read_b128 v[220:223], v148 offset:23552
	global_load_lds_dwordx4 v132, s[76:77]
	s_add_i32 m0, s0, 0x2000
	s_add_u32 s0, s76, 0x80000
	s_addc_u32 s1, s77, 0
	s_add_i32 s83, s84, s20
	global_load_lds_dwordx4 v136, s[76:77]
	s_mov_b32 m0, s83
	s_nop 0
	global_load_lds_dwordx4 v132, s[0:1]
	s_add_i32 m0, s83, 0x2000
	s_nop 0
	global_load_lds_dwordx4 v136, s[0:1]
	s_mov_b32 m0, s35
	s_nop 0
	global_load_lds_dwordx4 v130, s[78:79]
	s_mov_b32 m0, s37
	s_nop 0
	global_load_lds_dwordx4 v134, s[78:79]
	s_waitcnt vmcnt(8)
	s_waitcnt lgkmcnt(0)
	s_setprio 1
	s_barrier
	v_mfma_f32_16x16x32_bf16 v[94:97], v[150:153], v[192:195], v[94:97]
	v_mfma_f32_16x16x32_bf16 v[78:81], v[158:161], v[192:195], v[78:81]
	v_mfma_f32_16x16x32_bf16 v[90:93], v[150:153], v[200:203], v[90:93]
	v_mfma_f32_16x16x32_bf16 v[74:77], v[158:161], v[200:203], v[74:77]
	v_mfma_f32_16x16x32_bf16 v[86:89], v[150:153], v[208:211], v[86:89]
	v_mfma_f32_16x16x32_bf16 v[62:65], v[158:161], v[208:211], v[62:65]
	v_mfma_f32_16x16x32_bf16 v[82:85], v[150:153], v[216:219], v[82:85]
	v_mfma_f32_16x16x32_bf16 v[54:57], v[158:161], v[216:219], v[54:57]
	v_mfma_f32_16x16x32_bf16 v[94:97], v[154:157], v[196:199], v[94:97]
	v_mfma_f32_16x16x32_bf16 v[78:81], v[162:165], v[196:199], v[78:81]
	v_mfma_f32_16x16x32_bf16 v[90:93], v[154:157], v[204:207], v[90:93]
	v_mfma_f32_16x16x32_bf16 v[74:77], v[162:165], v[204:207], v[74:77]
	v_mfma_f32_16x16x32_bf16 v[86:89], v[154:157], v[212:215], v[86:89]
	v_mfma_f32_16x16x32_bf16 v[62:65], v[162:165], v[212:215], v[62:65]
	v_mfma_f32_16x16x32_bf16 v[82:85], v[154:157], v[220:223], v[82:85]
	v_mfma_f32_16x16x32_bf16 v[54:57], v[162:165], v[220:223], v[54:57]
	v_mfma_f32_16x16x32_bf16 v[30:33], v[166:169], v[192:195], v[30:33]
	v_mfma_f32_16x16x32_bf16 v[14:17], v[176:179], v[192:195], v[14:17]
	v_mfma_f32_16x16x32_bf16 v[26:29], v[166:169], v[200:203], v[26:29]
	v_mfma_f32_16x16x32_bf16 v[10:13], v[176:179], v[200:203], v[10:13]
	v_mfma_f32_16x16x32_bf16 v[22:25], v[166:169], v[208:211], v[22:25]
	v_mfma_f32_16x16x32_bf16 v[6:9], v[176:179], v[208:211], v[6:9]
	v_mfma_f32_16x16x32_bf16 v[18:21], v[166:169], v[216:219], v[18:21]
	v_mfma_f32_16x16x32_bf16 v[2:5], v[176:179], v[216:219], v[2:5]
	v_mfma_f32_16x16x32_bf16 v[30:33], v[172:175], v[196:199], v[30:33]
	v_mfma_f32_16x16x32_bf16 v[14:17], v[188:191], v[196:199], v[14:17]
	v_mfma_f32_16x16x32_bf16 v[26:29], v[172:175], v[204:207], v[26:29]
	v_mfma_f32_16x16x32_bf16 v[10:13], v[188:191], v[204:207], v[10:13]
	v_mfma_f32_16x16x32_bf16 v[22:25], v[172:175], v[212:215], v[22:25]
	v_mfma_f32_16x16x32_bf16 v[6:9], v[188:191], v[212:215], v[6:9]
	v_mfma_f32_16x16x32_bf16 v[18:21], v[172:175], v[220:223], v[18:21]
	v_mfma_f32_16x16x32_bf16 v[2:5], v[188:191], v[220:223], v[2:5]
	s_barrier
	s_setprio 0
	s_add_i32 s83, 0, 0x18000
	s_add_i32 s84, 0, 0x1c000
	ds_read_b128 v[150:153], v180 offset:32768
	ds_read_b128 v[154:157], v180 offset:33792
	ds_read_b128 v[158:161], v180 offset:34816
	ds_read_b128 v[162:165], v180 offset:35840
	ds_read_b128 v[166:169], v180 offset:49152
	ds_read_b128 v[172:175], v180 offset:50176
	ds_read_b128 v[176:179], v180 offset:51200
	ds_read_b128 v[188:191], v180 offset:52224
	s_add_u32 s0, s78, 0x80000
	s_addc_u32 s1, s79, 0
	s_mov_b32 m0, s43
	ds_read_b128 v[192:195], v148 offset:32768
	ds_read_b128 v[196:199], v148 offset:33792
	ds_read_b128 v[200:203], v148 offset:34816
	ds_read_b128 v[204:207], v148 offset:35840
	ds_read_b128 v[208:211], v148 offset:36864
	ds_read_b128 v[212:215], v148 offset:37888
	ds_read_b128 v[216:219], v148 offset:38912
	ds_read_b128 v[220:223], v148 offset:39936
	global_load_lds_dwordx4 v130, s[0:1]
	s_mov_b32 m0, s44
	s_nop 0
	global_load_lds_dwordx4 v134, s[0:1]
	s_waitcnt vmcnt(8)
	s_waitcnt lgkmcnt(0)
	s_setprio 1
	s_barrier
; #define PG8_STAGE(bufoff, gbase, voff) do { _Pragma("unroll") for (int _i = 0; _i < 2; ++_i) \
;         __builtin_amdgcn_global_load_lds((const unsigned*)((const char*)(gbase) + (voff)[_i]), (PG8_LAS unsigned*)(lds + (bufoff) + ldsw + _i * 8192), 16, 0, 0); } while (0)
; #define PG8_LDA(dst, b, h) do { _Pragma("unroll") for (int m = 0; m < 4; ++m) _Pragma("unroll") for (int k = 0; k < 2; ++k) dst[m][k] = *(const PG8_LAS bf16x8*)(lds + PG8_SA(b, h) + aoff + m * 2048 + k * 1024); } while (0)
; #define PG8_WAIT_V(n) asm volatile("s_waitcnt vmcnt(" #n ")" ::: "memory")
; #define PG8_WAIT_L(n) asm volatile("s_waitcnt lgkmcnt(" #n ")" ::: "memory")
; #define PG8_BAR __builtin_amdgcn_s_barrier()
; #define PG8_SCHED __builtin_amdgcn_sched_barrier(0)
;     ...
;             PG8_WAIT_V(8); PG8_WAIT_L(0); PG8_BAR; PG8_MMA(0, 0, At, B0); PG8_MMA(0, 1, At, B1); PG8_BAR; PG8_SCHED;
;             PG8_LDA(At, 1, 1); PG8_STAGE(PG8_SB(1, 0), b3, voffB); PG8_STAGE(PG8_SB(1, 1), b3 + hstep, voffB); PG8_STAGE(PG8_SA(1, 0), a3, voffA);
;             PG8_WAIT_V(8); PG8_WAIT_L(0); PG8_BAR; PG8_MMA(1, 0, At, B0); PG8_MMA(1, 1, At, B1); PG8_BAR; PG8_SCHED;
	v_mfma_f32_16x16x32_bf16 v[126:129], v[150:153], v[192:195], v[126:129]
	v_mfma_f32_16x16x32_bf16 v[110:113], v[158:161], v[192:195], v[110:113]
	v_mfma_f32_16x16x32_bf16 v[122:125], v[150:153], v[200:203], v[122:125]
	v_mfma_f32_16x16x32_bf16 v[106:109], v[158:161], v[200:203], v[106:109]
	v_mfma_f32_16x16x32_bf16 v[118:121], v[150:153], v[208:211], v[118:121]
	v_mfma_f32_16x16x32_bf16 v[102:105], v[158:161], v[208:211], v[102:105]
	v_mfma_f32_16x16x32_bf16 v[114:117], v[150:153], v[216:219], v[114:117]
	v_mfma_f32_16x16x32_bf16 v[98:101], v[158:161], v[216:219], v[98:101]
	v_mfma_f32_16x16x32_bf16 v[126:129], v[154:157], v[196:199], v[126:129]
	v_mfma_f32_16x16x32_bf16 v[110:113], v[162:165], v[196:199], v[110:113]
	v_mfma_f32_16x16x32_bf16 v[122:125], v[154:157], v[204:207], v[122:125]
	v_mfma_f32_16x16x32_bf16 v[106:109], v[162:165], v[204:207], v[106:109]
	v_mfma_f32_16x16x32_bf16 v[118:121], v[154:157], v[212:215], v[118:121]
	v_mfma_f32_16x16x32_bf16 v[102:105], v[162:165], v[212:215], v[102:105]
	v_mfma_f32_16x16x32_bf16 v[114:117], v[154:157], v[220:223], v[114:117]
	v_mfma_f32_16x16x32_bf16 v[98:101], v[162:165], v[220:223], v[98:101]
	v_mfma_f32_16x16x32_bf16 v[70:73], v[166:169], v[192:195], v[70:73]
	v_mfma_f32_16x16x32_bf16 v[50:53], v[176:179], v[192:195], v[50:53]
	v_mfma_f32_16x16x32_bf16 v[66:69], v[166:169], v[200:203], v[66:69]
	v_mfma_f32_16x16x32_bf16 v[42:45], v[176:179], v[200:203], v[42:45]
	v_mfma_f32_16x16x32_bf16 v[58:61], v[166:169], v[208:211], v[58:61]
	v_mfma_f32_16x16x32_bf16 v[38:41], v[176:179], v[208:211], v[38:41]
	v_mfma_f32_16x16x32_bf16 v[46:49], v[166:169], v[216:219], v[46:49]
	v_mfma_f32_16x16x32_bf16 v[34:37], v[176:179], v[216:219], v[34:37]
	v_mfma_f32_16x16x32_bf16 v[70:73], v[172:175], v[196:199], v[70:73]
	v_mfma_f32_16x16x32_bf16 v[50:53], v[188:191], v[196:199], v[50:53]
	v_mfma_f32_16x16x32_bf16 v[66:69], v[172:175], v[204:207], v[66:69]
	v_mfma_f32_16x16x32_bf16 v[42:45], v[188:191], v[204:207], v[42:45]
	v_mfma_f32_16x16x32_bf16 v[58:61], v[172:175], v[212:215], v[58:61]
	v_mfma_f32_16x16x32_bf16 v[38:41], v[188:191], v[212:215], v[38:41]
	v_mfma_f32_16x16x32_bf16 v[46:49], v[172:175], v[220:223], v[46:49]
	v_mfma_f32_16x16x32_bf16 v[34:37], v[188:191], v[220:223], v[34:37]
	s_barrier
	s_setprio 0
	s_add_i32 s0, s83, s20
	s_mov_b32 m0, s0
	ds_read_b128 v[192:195], v148 offset:49152
	ds_read_b128 v[196:199], v148 offset:50176
	ds_read_b128 v[200:203], v148 offset:51200
	ds_read_b128 v[204:207], v148 offset:52224
	ds_read_b128 v[208:211], v148 offset:53248
	ds_read_b128 v[212:215], v148 offset:54272
	ds_read_b128 v[216:219], v148 offset:55296
	ds_read_b128 v[220:223], v148 offset:56320
	s_add_u32 s100, s76, 0x80
	s_addc_u32 s101, s77, 0
	global_load_lds_dwordx4 v132, s[100:101]
	s_add_i32 m0, s0, 0x2000
	s_add_u32 s0, s76, 0x80080
	s_addc_u32 s1, s77, 0
	s_add_i32 s76, s84, s20
	global_load_lds_dwordx4 v136, s[100:101]
	s_mov_b32 m0, s76
	s_nop 0
	global_load_lds_dwordx4 v132, s[0:1]
	s_add_i32 m0, s76, 0x2000
	s_nop 0
	global_load_lds_dwordx4 v136, s[0:1]
	s_mov_b32 m0, s48
	s_nop 0
	s_add_u32 s100, s78, 0x80
	s_addc_u32 s101, s79, 0
	global_load_lds_dwordx4 v130, s[100:101]
	s_mov_b32 m0, s49
	s_nop 0
	global_load_lds_dwordx4 v134, s[100:101]
	s_waitcnt vmcnt(8)
	s_waitcnt lgkmcnt(0)
	s_setprio 1
	s_barrier
	v_mfma_f32_16x16x32_bf16 v[94:97], v[150:153], v[192:195], v[94:97]
	v_mfma_f32_16x16x32_bf16 v[78:81], v[158:161], v[192:195], v[78:81]
	v_mfma_f32_16x16x32_bf16 v[90:93], v[150:153], v[200:203], v[90:93]
	v_mfma_f32_16x16x32_bf16 v[74:77], v[158:161], v[200:203], v[74:77]
	v_mfma_f32_16x16x32_bf16 v[86:89], v[150:153], v[208:211], v[86:89]
	v_mfma_f32_16x16x32_bf16 v[62:65], v[158:161], v[208:211], v[62:65]
	v_mfma_f32_16x16x32_bf16 v[82:85], v[150:153], v[216:219], v[82:85]
	v_mfma_f32_16x16x32_bf16 v[54:57], v[158:161], v[216:219], v[54:57]
	v_mfma_f32_16x16x32_bf16 v[94:97], v[154:157], v[196:199], v[94:97]
	v_mfma_f32_16x16x32_bf16 v[78:81], v[162:165], v[196:199], v[78:81]
	v_mfma_f32_16x16x32_bf16 v[90:93], v[154:157], v[204:207], v[90:93]
	v_mfma_f32_16x16x32_bf16 v[74:77], v[162:165], v[204:207], v[74:77]
	v_mfma_f32_16x16x32_bf16 v[86:89], v[154:157], v[212:215], v[86:89]
	v_mfma_f32_16x16x32_bf16 v[62:65], v[162:165], v[212:215], v[62:65]
	v_mfma_f32_16x16x32_bf16 v[82:85], v[154:157], v[220:223], v[82:85]
	v_mfma_f32_16x16x32_bf16 v[54:57], v[162:165], v[220:223], v[54:57]
	v_mfma_f32_16x16x32_bf16 v[30:33], v[166:169], v[192:195], v[30:33]
	v_mfma_f32_16x16x32_bf16 v[14:17], v[176:179], v[192:195], v[14:17]
	v_mfma_f32_16x16x32_bf16 v[26:29], v[166:169], v[200:203], v[26:29]
	v_mfma_f32_16x16x32_bf16 v[10:13], v[176:179], v[200:203], v[10:13]
	v_mfma_f32_16x16x32_bf16 v[22:25], v[166:169], v[208:211], v[22:25]
	v_mfma_f32_16x16x32_bf16 v[6:9], v[176:179], v[208:211], v[6:9]
	v_mfma_f32_16x16x32_bf16 v[18:21], v[166:169], v[216:219], v[18:21]
	v_mfma_f32_16x16x32_bf16 v[2:5], v[176:179], v[216:219], v[2:5]
	v_mfma_f32_16x16x32_bf16 v[30:33], v[172:175], v[196:199], v[30:33]
	v_mfma_f32_16x16x32_bf16 v[14:17], v[188:191], v[196:199], v[14:17]
	v_mfma_f32_16x16x32_bf16 v[26:29], v[172:175], v[204:207], v[26:29]
	v_mfma_f32_16x16x32_bf16 v[10:13], v[188:191], v[204:207], v[10:13]
	v_mfma_f32_16x16x32_bf16 v[22:25], v[172:175], v[212:215], v[22:25]
	v_mfma_f32_16x16x32_bf16 v[6:9], v[188:191], v[212:215], v[6:9]
	v_mfma_f32_16x16x32_bf16 v[18:21], v[172:175], v[220:223], v[18:21]
	v_mfma_f32_16x16x32_bf16 v[2:5], v[188:191], v[220:223], v[2:5]
	s_barrier
	s_setprio 0
	s_add_i32 s82, s82, 2
	s_add_u32 s74, s74, 0x100
	s_addc_u32 s75, s75, 0
	s_add_u32 s80, s80, 0x100
	s_addc_u32 s81, s81, 0
	s_cmp_gt_u32 s82, 29
	s_cbranch_scc0 .LBB0_596
	s_and_b64 vcc, exec, s[62:63]
	s_cbranch_vccz .LBB0_599
	s_barrier

;     __host__ __device__ bool next(int i, Unit& u) const { const long L = (long)i * G + c; if (L >= lim) return false; unit_of((int)L, u); return true; }
;     __device__ __forceinline__ bool next(int i, Unit& v) const { if (i != 0) return false; v = u; return true; }
; #define PG8_STAGE(bufoff, gbase, voff) do { _Pragma("unroll") for (int _i = 0; _i < 2; ++_i) \
;         __builtin_amdgcn_global_load_lds((const unsigned*)((const char*)(gbase) + (voff)[_i]), (PG8_LAS unsigned*)(lds + (bufoff) + ldsw + _i * 8192), 16, 0, 0); } while (0)
; #define PG8_LDA(dst, b, h) do { _Pragma("unroll") for (int m = 0; m < 4; ++m) _Pragma("unroll") for (int k = 0; k < 2; ++k) dst[m][k] = *(const PG8_LAS bf16x8*)(lds + PG8_SA(b, h) + aoff + m * 2048 + k * 1024); } while (0)
;     ...
;         const bool has_next = S.next(ui + 1, nxt);
;         if constexpr (TP == 3) { if (ui > 0) tp_acc += __builtin_amdgcn_s_memrealtime() - tp3; }
;         const char* nA = has_next ? (const char*)g.A + (size_t)nxt.pm * tstep : cA; const char* nB = has_next ? (const char*)g.Bt + (size_t)nxt.pn * tstep : cB;
;         for (int t = 0; t < nt * KREP; t += 2) {
;             const bool last = (t == nt * KREP - 2);
;             const int t1w = KREP > 1 ? ((t + 1) & (nt - 1)) : t + 1, t2w = KREP > 1 ? ((t + 2) & (nt - 1)) : t + 2;
;             const char* a1 = cA + (size_t)t1w * kstep;
;             const char* a2 = last ? nA : cA + (size_t)t2w * kstep; const char* b2 = last ? nB : cB + (size_t)t2w * kstep;
;             const char* a3 = a2 + kstep; const char* b3 = b2 + kstep;
;             if (last && has_next) S.a_ready(nxt);
;             const int relax = __builtin_amdgcn_readfirstlane((MK_RELAXW && t == 0 && ui > 0) ? 1 : 0);
;             if constexpr (SP2) {
;             PG8_LDB(B0, 0, 0); PG8_LDB(B1, 0, 1); PG8_SCHED; PG8_LDA(At, 0, 0); PG8_STAGE(PG8_SA(1, 1), a1 + hstep, voffA);
;             PG8_WAIT_V_SEL(relax);
;             PG8_WAIT_L(0); PG8_BAR; PG8_MMA(0, 0, At, B0); PG8_MMA(0, 1, At, B1); PG8_BAR; PG8_SCHED;
;     ...
; #pragma unroll
;         for (int a = 0; a < 2; ++a)
; #pragma unroll
;             for (int b = 0; b < 2; ++b)
; #pragma unroll
;                 for (int m = 0; m < 4; ++m)
; #pragma unroll
;                     for (int n = 0; n < 2; ++n) acc[a][b][m][n] = (f32x4){0.f, 0.f, 0.f, 0.f};
;         cur = nxt; cA = nA; cB = nB; ++ui;
.LBB0_1169:
	s_ashr_i32 s69, s68, 31
	s_lshl_b64 s[0:1], s[68:69], 20
	s_add_u32 s70, s35, s0
	s_addc_u32 s71, s37, s1
	s_and_b64 s[0:1], s[4:5], exec
	s_cselect_b32 s40, s71, s79
	s_cselect_b32 s41, s70, s78
	s_ashr_i32 s67, s66, 31
	s_lshl_b64 s[0:1], s[66:67], 20
	s_add_u32 s72, s43, s0
	s_addc_u32 s73, s44, s1
	s_and_b64 s[0:1], s[4:5], exec
	s_cselect_b32 s67, s73, s81
	s_cselect_b32 s69, s72, s80
	s_add_u32 s78, s78, 0x80080
	s_addc_u32 s79, s79, 0
	s_add_u32 s75, s80, 0x100
	v_mov_b64_e32 v[2:3], 0
	v_mov_b64_e32 v[4:5], 0
	v_mov_b64_e32 v[6:7], 0
	v_mov_b64_e32 v[8:9], 0
	v_mov_b64_e32 v[10:11], 0
	v_mov_b64_e32 v[12:13], 0
	v_mov_b64_e32 v[14:15], 0
	v_mov_b64_e32 v[16:17], 0
	v_mov_b64_e32 v[18:19], 0
	v_mov_b64_e32 v[20:21], 0
	v_mov_b64_e32 v[22:23], 0
	v_mov_b64_e32 v[24:25], 0
	v_mov_b64_e32 v[26:27], 0
	v_mov_b64_e32 v[28:29], 0
	v_mov_b64_e32 v[30:31], 0
	v_mov_b64_e32 v[32:33], 0
	v_mov_b64_e32 v[34:35], 0
	v_mov_b64_e32 v[36:37], 0
	v_mov_b64_e32 v[38:39], 0
	v_mov_b64_e32 v[40:41], 0
	v_mov_b64_e32 v[42:43], 0
	v_mov_b64_e32 v[44:45], 0
	v_mov_b64_e32 v[46:47], 0
	v_mov_b64_e32 v[48:49], 0
	v_mov_b64_e32 v[50:51], 0
	v_mov_b64_e32 v[52:53], 0
	v_mov_b64_e32 v[54:55], 0
	v_mov_b64_e32 v[56:57], 0
	v_mov_b64_e32 v[58:59], 0
	v_mov_b64_e32 v[60:61], 0
	v_mov_b64_e32 v[62:63], 0
	v_mov_b64_e32 v[64:65], 0
	v_mov_b64_e32 v[66:67], 0
	v_mov_b64_e32 v[68:69], 0
	v_mov_b64_e32 v[70:71], 0
	v_mov_b64_e32 v[72:73], 0
	v_mov_b64_e32 v[74:75], 0
	v_mov_b64_e32 v[76:77], 0
	v_mov_b64_e32 v[78:79], 0
	v_mov_b64_e32 v[80:81], 0
	v_mov_b64_e32 v[82:83], 0
	v_mov_b64_e32 v[84:85], 0
	v_mov_b64_e32 v[86:87], 0
	v_mov_b64_e32 v[88:89], 0
	v_mov_b64_e32 v[106:107], 0
	v_mov_b64_e32 v[108:109], 0
	v_mov_b64_e32 v[110:111], 0
	v_mov_b64_e32 v[112:113], 0
	v_mov_b64_e32 v[114:115], 0
	v_mov_b64_e32 v[116:117], 0
	v_mov_b64_e32 v[118:119], 0
	v_mov_b64_e32 v[120:121], 0
	v_mov_b64_e32 v[122:123], 0
	v_mov_b64_e32 v[124:125], 0
	v_mov_b64_e32 v[126:127], 0
	v_mov_b64_e32 v[128:129], 0
	v_mov_b64_e32 v[130:131], 0
	v_mov_b64_e32 v[132:133], 0
	v_mov_b64_e32 v[134:135], 0
	v_mov_b64_e32 v[136:137], 0
	v_mov_b64_e32 v[138:139], 0
	v_mov_b64_e32 v[140:141], 0
	v_mov_b64_e32 v[142:143], 0
	v_mov_b64_e32 v[144:145], 0
	s_addc_u32 s77, s81, 0
	s_mov_b32 s84, -2
	s_waitcnt lgkmcnt(0)
	v_add_u32_e32 v184, 0x10000, v224
.LBB0_1170:
	s_add_u32 s0, s78, 0xfff80080
	s_addc_u32 s1, s79, -1
	s_add_i32 s85, 0, 0x10000
	s_cmp_eq_u32 s84, 28
	s_cselect_b32 s83, s40, s1
	s_cselect_b32 s82, s41, s0
	s_cselect_b32 s81, s67, s77
	s_cselect_b32 s80, s69, s75
	s_add_i32 s86, 0, 0x14000
	ds_read_b128 v[90:93], v184
	ds_read_b128 v[94:97], v184 offset:1024
	ds_read_b128 v[98:101], v184 offset:2048
	ds_read_b128 v[102:105], v184 offset:3072
	ds_read_b128 v[146:149], v184 offset:16384
	ds_read_b128 v[150:153], v184 offset:17408
	ds_read_b128 v[154:157], v184 offset:18432
	ds_read_b128 v[158:161], v184 offset:19456
	s_add_i32 m0, s45, 0xc000
	ds_read_b128 v[162:165], v227
	ds_read_b128 v[166:169], v227 offset:1024
	ds_read_b128 v[188:191], v227 offset:2048
	ds_read_b128 v[192:195], v227 offset:3072
	ds_read_b128 v[196:199], v227 offset:4096
	ds_read_b128 v[200:203], v227 offset:5120
	ds_read_b128 v[204:207], v227 offset:6144
	ds_read_b128 v[208:211], v227 offset:7168
	global_load_lds_dwordx4 v178, s[78:79]
	s_add_i32 m0, s45, 0xe000
	s_nop 0
	global_load_lds_dwordx4 v180, s[78:79]
	s_waitcnt vmcnt(8)
	s_waitcnt lgkmcnt(0)
	s_setprio 1
	s_barrier
	v_mfma_f32_16x16x32_bf16 v[142:145], v[90:93], v[162:165], v[142:145]
	v_mfma_f32_16x16x32_bf16 v[138:141], v[98:101], v[162:165], v[138:141]
	v_mfma_f32_16x16x32_bf16 v[126:129], v[90:93], v[188:191], v[126:129]
	v_mfma_f32_16x16x32_bf16 v[122:125], v[98:101], v[188:191], v[122:125]
	v_mfma_f32_16x16x32_bf16 v[110:113], v[90:93], v[196:199], v[110:113]
	v_mfma_f32_16x16x32_bf16 v[106:109], v[98:101], v[196:199], v[106:109]
	v_mfma_f32_16x16x32_bf16 v[78:81], v[90:93], v[204:207], v[78:81]
	v_mfma_f32_16x16x32_bf16 v[74:77], v[98:101], v[204:207], v[74:77]
	v_mfma_f32_16x16x32_bf16 v[142:145], v[94:97], v[166:169], v[142:145]
	v_mfma_f32_16x16x32_bf16 v[138:141], v[102:105], v[166:169], v[138:141]
	v_mfma_f32_16x16x32_bf16 v[126:129], v[94:97], v[192:195], v[126:129]
	v_mfma_f32_16x16x32_bf16 v[122:125], v[102:105], v[192:195], v[122:125]
	v_mfma_f32_16x16x32_bf16 v[110:113], v[94:97], v[200:203], v[110:113]
	v_mfma_f32_16x16x32_bf16 v[106:109], v[102:105], v[200:203], v[106:109]
	v_mfma_f32_16x16x32_bf16 v[78:81], v[94:97], v[208:211], v[78:81]
	v_mfma_f32_16x16x32_bf16 v[74:77], v[102:105], v[208:211], v[74:77]
	v_mfma_f32_16x16x32_bf16 v[134:137], v[146:149], v[162:165], v[134:137]
	v_mfma_f32_16x16x32_bf16 v[130:133], v[154:157], v[162:165], v[130:133]
	v_mfma_f32_16x16x32_bf16 v[118:121], v[146:149], v[188:191], v[118:121]
	v_mfma_f32_16x16x32_bf16 v[114:117], v[154:157], v[188:191], v[114:117]
	v_mfma_f32_16x16x32_bf16 v[86:89], v[146:149], v[196:199], v[86:89]
	v_mfma_f32_16x16x32_bf16 v[82:85], v[154:157], v[196:199], v[82:85]
	v_mfma_f32_16x16x32_bf16 v[70:73], v[146:149], v[204:207], v[70:73]
	v_mfma_f32_16x16x32_bf16 v[66:69], v[154:157], v[204:207], v[66:69]
	v_mfma_f32_16x16x32_bf16 v[134:137], v[150:153], v[166:169], v[134:137]
	v_mfma_f32_16x16x32_bf16 v[130:133], v[158:161], v[166:169], v[130:133]
	v_mfma_f32_16x16x32_bf16 v[118:121], v[150:153], v[192:195], v[118:121]
	v_mfma_f32_16x16x32_bf16 v[114:117], v[158:161], v[192:195], v[114:117]
	v_mfma_f32_16x16x32_bf16 v[86:89], v[150:153], v[200:203], v[86:89]
	v_mfma_f32_16x16x32_bf16 v[82:85], v[158:161], v[200:203], v[82:85]
	v_mfma_f32_16x16x32_bf16 v[70:73], v[150:153], v[208:211], v[70:73]
	v_mfma_f32_16x16x32_bf16 v[66:69], v[158:161], v[208:211], v[66:69]
	s_barrier
; #define PG8_STAGE(bufoff, gbase, voff) do { _Pragma("unroll") for (int _i = 0; _i < 2; ++_i) \
;         __builtin_amdgcn_global_load_lds((const unsigned*)((const char*)(gbase) + (voff)[_i]), (PG8_LAS unsigned*)(lds + (bufoff) + ldsw + _i * 8192), 16, 0, 0); } while (0)
; #define PG8_LDA(dst, b, h) do { _Pragma("unroll") for (int m = 0; m < 4; ++m) _Pragma("unroll") for (int k = 0; k < 2; ++k) dst[m][k] = *(const PG8_LAS bf16x8*)(lds + PG8_SA(b, h) + aoff + m * 2048 + k * 1024); } while (0)
; #define PG8_LDB(dst, b, h) do { _Pragma("unroll") for (int n = 0; n < 2; ++n) _Pragma("unroll") for (int k = 0; k < 2; ++k) dst[n][k] = *(const PG8_LAS bf16x8*)(lds + PG8_SB(b, h) + boff + n * 2048 + k * 1024); } while (0)
; #define PG8_WAIT_V(n) asm volatile("s_waitcnt vmcnt(" #n ")" ::: "memory")
; #define PG8_WAIT_L(n) asm volatile("s_waitcnt lgkmcnt(" #n ")" ::: "memory")
; #define PG8_WAIT_V_SEL(sel) asm volatile("s_cmp_eq_u32 %0, 0\n\ts_cbranch_scc1 .Lw8_%=\n\ts_waitcnt vmcnt(22)\n\ts_branch .Lwd_%=\n.Lw8_%=:\n\ts_waitcnt vmcnt(8)\n.Lwd_%=:" :: "s"(sel) : "memory", "scc")
; #define PG8_BAR __builtin_amdgcn_s_barrier()
; #define PG8_SCHED __builtin_amdgcn_sched_barrier(0)
;     ...
;             PG8_LDA(At, 0, 1); PG8_STAGE(PG8_SB(0, 0), b2, voffB); PG8_STAGE(PG8_SB(0, 1), b2 + hstep, voffB); PG8_STAGE(PG8_SA(0, 0), a2, voffA);
;             PG8_WAIT_V_SEL(relax);
;             PG8_WAIT_L(0); PG8_BAR; PG8_MMA(1, 0, At, B0); PG8_MMA(1, 1, At, B1); PG8_BAR; PG8_SCHED;
;             PG8_LDB(B0, 1, 0); PG8_LDB(B1, 1, 1); PG8_SCHED; PG8_LDA(At, 1, 0); PG8_STAGE(PG8_SA(0, 1), a2 + hstep, voffA);
;             PG8_WAIT_V(8); PG8_WAIT_L(0); PG8_BAR; PG8_MMA(0, 0, At, B0); PG8_MMA(0, 1, At, B1); PG8_BAR; PG8_SCHED;
	s_setprio 0
	s_add_i32 s0, s85, s33
	s_mov_b32 m0, s0
	ds_read_b128 v[162:165], v227 offset:16384
	ds_read_b128 v[166:169], v227 offset:17408
	ds_read_b128 v[188:191], v227 offset:18432
	ds_read_b128 v[192:195], v227 offset:19456
	ds_read_b128 v[196:199], v227 offset:20480
	ds_read_b128 v[200:203], v227 offset:21504
	ds_read_b128 v[204:207], v227 offset:22528
	ds_read_b128 v[208:211], v227 offset:23552
	global_load_lds_dwordx4 v182, s[80:81]
	s_add_i32 m0, s0, 0x2000
	s_add_u32 s0, s80, 0x80000
	s_addc_u32 s1, s81, 0
	s_add_i32 s85, s86, s33
	global_load_lds_dwordx4 v176, s[80:81]
	s_mov_b32 m0, s85
	s_nop 0
	global_load_lds_dwordx4 v182, s[0:1]
	s_add_i32 m0, s85, 0x2000
	s_nop 0
	global_load_lds_dwordx4 v176, s[0:1]
	s_mov_b32 m0, s45
	s_nop 0
	global_load_lds_dwordx4 v172, s[82:83]
	s_mov_b32 m0, s46
	s_nop 0
	global_load_lds_dwordx4 v174, s[82:83]
	s_waitcnt vmcnt(8)
	s_waitcnt lgkmcnt(0)
	s_setprio 1
	s_barrier
	v_mfma_f32_16x16x32_bf16 v[62:65], v[90:93], v[162:165], v[62:65]
	v_mfma_f32_16x16x32_bf16 v[58:61], v[98:101], v[162:165], v[58:61]
	v_mfma_f32_16x16x32_bf16 v[46:49], v[90:93], v[188:191], v[46:49]
	v_mfma_f32_16x16x32_bf16 v[42:45], v[98:101], v[188:191], v[42:45]
	v_mfma_f32_16x16x32_bf16 v[30:33], v[90:93], v[196:199], v[30:33]
	v_mfma_f32_16x16x32_bf16 v[26:29], v[98:101], v[196:199], v[26:29]
	v_mfma_f32_16x16x32_bf16 v[14:17], v[90:93], v[204:207], v[14:17]
	v_mfma_f32_16x16x32_bf16 v[10:13], v[98:101], v[204:207], v[10:13]
	v_mfma_f32_16x16x32_bf16 v[62:65], v[94:97], v[166:169], v[62:65]
	v_mfma_f32_16x16x32_bf16 v[58:61], v[102:105], v[166:169], v[58:61]
	v_mfma_f32_16x16x32_bf16 v[46:49], v[94:97], v[192:195], v[46:49]
	v_mfma_f32_16x16x32_bf16 v[42:45], v[102:105], v[192:195], v[42:45]
	v_mfma_f32_16x16x32_bf16 v[30:33], v[94:97], v[200:203], v[30:33]
	v_mfma_f32_16x16x32_bf16 v[26:29], v[102:105], v[200:203], v[26:29]
	v_mfma_f32_16x16x32_bf16 v[14:17], v[94:97], v[208:211], v[14:17]
	v_mfma_f32_16x16x32_bf16 v[10:13], v[102:105], v[208:211], v[10:13]
	v_mfma_f32_16x16x32_bf16 v[54:57], v[146:149], v[162:165], v[54:57]
	v_mfma_f32_16x16x32_bf16 v[50:53], v[154:157], v[162:165], v[50:53]
	v_mfma_f32_16x16x32_bf16 v[38:41], v[146:149], v[188:191], v[38:41]
	v_mfma_f32_16x16x32_bf16 v[34:37], v[154:157], v[188:191], v[34:37]
	v_mfma_f32_16x16x32_bf16 v[22:25], v[146:149], v[196:199], v[22:25]
	v_mfma_f32_16x16x32_bf16 v[18:21], v[154:157], v[196:199], v[18:21]
	v_mfma_f32_16x16x32_bf16 v[6:9], v[146:149], v[204:207], v[6:9]
	v_mfma_f32_16x16x32_bf16 v[2:5], v[154:157], v[204:207], v[2:5]
	v_mfma_f32_16x16x32_bf16 v[54:57], v[150:153], v[166:169], v[54:57]
	v_mfma_f32_16x16x32_bf16 v[50:53], v[158:161], v[166:169], v[50:53]
	v_mfma_f32_16x16x32_bf16 v[38:41], v[150:153], v[192:195], v[38:41]
	v_mfma_f32_16x16x32_bf16 v[34:37], v[158:161], v[192:195], v[34:37]
	v_mfma_f32_16x16x32_bf16 v[22:25], v[150:153], v[200:203], v[22:25]
	v_mfma_f32_16x16x32_bf16 v[18:21], v[158:161], v[200:203], v[18:21]
	v_mfma_f32_16x16x32_bf16 v[6:9], v[150:153], v[208:211], v[6:9]
	v_mfma_f32_16x16x32_bf16 v[2:5], v[158:161], v[208:211], v[2:5]
	s_barrier
	s_setprio 0
	s_add_i32 s85, 0, 0x18000
	s_add_i32 s86, 0, 0x1c000
	ds_read_b128 v[90:93], v184 offset:32768
	ds_read_b128 v[94:97], v184 offset:33792
	ds_read_b128 v[98:101], v184 offset:34816
	ds_read_b128 v[102:105], v184 offset:35840
	ds_read_b128 v[146:149], v184 offset:49152
	ds_read_b128 v[150:153], v184 offset:50176
	ds_read_b128 v[154:157], v184 offset:51200
	ds_read_b128 v[158:161], v184 offset:52224
	s_add_u32 s0, s82, 0x80000
	s_addc_u32 s1, s83, 0
	s_mov_b32 m0, s47
	ds_read_b128 v[162:165], v227 offset:32768
	ds_read_b128 v[166:169], v227 offset:33792
	ds_read_b128 v[188:191], v227 offset:34816
	ds_read_b128 v[192:195], v227 offset:35840
	ds_read_b128 v[196:199], v227 offset:36864
	ds_read_b128 v[200:203], v227 offset:37888
	ds_read_b128 v[204:207], v227 offset:38912
	ds_read_b128 v[208:211], v227 offset:39936
	global_load_lds_dwordx4 v172, s[0:1]
	s_mov_b32 m0, s48
	s_nop 0
	global_load_lds_dwordx4 v174, s[0:1]
	s_waitcnt vmcnt(8)
	s_waitcnt lgkmcnt(0)
	s_setprio 1
	s_barrier
; #define PG8_STAGE(bufoff, gbase, voff) do { _Pragma("unroll") for (int _i = 0; _i < 2; ++_i) \
;         __builtin_amdgcn_global_load_lds((const unsigned*)((const char*)(gbase) + (voff)[_i]), (PG8_LAS unsigned*)(lds + (bufoff) + ldsw + _i * 8192), 16, 0, 0); } while (0)
; #define PG8_LDA(dst, b, h) do { _Pragma("unroll") for (int m = 0; m < 4; ++m) _Pragma("unroll") for (int k = 0; k < 2; ++k) dst[m][k] = *(const PG8_LAS bf16x8*)(lds + PG8_SA(b, h) + aoff + m * 2048 + k * 1024); } while (0)
; #define PG8_WAIT_V(n) asm volatile("s_waitcnt vmcnt(" #n ")" ::: "memory")
; #define PG8_WAIT_L(n) asm volatile("s_waitcnt lgkmcnt(" #n ")" ::: "memory")
; #define PG8_BAR __builtin_amdgcn_s_barrier()
; #define PG8_SCHED __builtin_amdgcn_sched_barrier(0)
;     ...
;             PG8_WAIT_V(8); PG8_WAIT_L(0); PG8_BAR; PG8_MMA(0, 0, At, B0); PG8_MMA(0, 1, At, B1); PG8_BAR; PG8_SCHED;
;             PG8_LDA(At, 1, 1); PG8_STAGE(PG8_SB(1, 0), b3, voffB); PG8_STAGE(PG8_SB(1, 1), b3 + hstep, voffB); PG8_STAGE(PG8_SA(1, 0), a3, voffA);
;             PG8_WAIT_V(8); PG8_WAIT_L(0); PG8_BAR; PG8_MMA(1, 0, At, B0); PG8_MMA(1, 1, At, B1); PG8_BAR; PG8_SCHED;
	v_mfma_f32_16x16x32_bf16 v[142:145], v[90:93], v[162:165], v[142:145]
	v_mfma_f32_16x16x32_bf16 v[138:141], v[98:101], v[162:165], v[138:141]
	v_mfma_f32_16x16x32_bf16 v[126:129], v[90:93], v[188:191], v[126:129]
	v_mfma_f32_16x16x32_bf16 v[122:125], v[98:101], v[188:191], v[122:125]
	v_mfma_f32_16x16x32_bf16 v[110:113], v[90:93], v[196:199], v[110:113]
	v_mfma_f32_16x16x32_bf16 v[106:109], v[98:101], v[196:199], v[106:109]
	v_mfma_f32_16x16x32_bf16 v[78:81], v[90:93], v[204:207], v[78:81]
	v_mfma_f32_16x16x32_bf16 v[74:77], v[98:101], v[204:207], v[74:77]
	v_mfma_f32_16x16x32_bf16 v[142:145], v[94:97], v[166:169], v[142:145]
	v_mfma_f32_16x16x32_bf16 v[138:141], v[102:105], v[166:169], v[138:141]
	v_mfma_f32_16x16x32_bf16 v[126:129], v[94:97], v[192:195], v[126:129]
	v_mfma_f32_16x16x32_bf16 v[122:125], v[102:105], v[192:195], v[122:125]
	v_mfma_f32_16x16x32_bf16 v[110:113], v[94:97], v[200:203], v[110:113]
	v_mfma_f32_16x16x32_bf16 v[106:109], v[102:105], v[200:203], v[106:109]
	v_mfma_f32_16x16x32_bf16 v[78:81], v[94:97], v[208:211], v[78:81]
	v_mfma_f32_16x16x32_bf16 v[74:77], v[102:105], v[208:211], v[74:77]
	v_mfma_f32_16x16x32_bf16 v[134:137], v[146:149], v[162:165], v[134:137]
	v_mfma_f32_16x16x32_bf16 v[130:133], v[154:157], v[162:165], v[130:133]
	v_mfma_f32_16x16x32_bf16 v[118:121], v[146:149], v[188:191], v[118:121]
	v_mfma_f32_16x16x32_bf16 v[114:117], v[154:157], v[188:191], v[114:117]
	v_mfma_f32_16x16x32_bf16 v[86:89], v[146:149], v[196:199], v[86:89]
	v_mfma_f32_16x16x32_bf16 v[82:85], v[154:157], v[196:199], v[82:85]
	v_mfma_f32_16x16x32_bf16 v[70:73], v[146:149], v[204:207], v[70:73]
	v_mfma_f32_16x16x32_bf16 v[66:69], v[154:157], v[204:207], v[66:69]
	v_mfma_f32_16x16x32_bf16 v[134:137], v[150:153], v[166:169], v[134:137]
	v_mfma_f32_16x16x32_bf16 v[130:133], v[158:161], v[166:169], v[130:133]
	v_mfma_f32_16x16x32_bf16 v[118:121], v[150:153], v[192:195], v[118:121]
	v_mfma_f32_16x16x32_bf16 v[114:117], v[158:161], v[192:195], v[114:117]
	v_mfma_f32_16x16x32_bf16 v[86:89], v[150:153], v[200:203], v[86:89]
	v_mfma_f32_16x16x32_bf16 v[82:85], v[158:161], v[200:203], v[82:85]
	v_mfma_f32_16x16x32_bf16 v[70:73], v[150:153], v[208:211], v[70:73]
	v_mfma_f32_16x16x32_bf16 v[66:69], v[158:161], v[208:211], v[66:69]
	s_barrier
	s_setprio 0
	s_add_i32 s0, s85, s33
	s_mov_b32 m0, s0
	ds_read_b128 v[162:165], v227 offset:49152
	ds_read_b128 v[166:169], v227 offset:50176
	ds_read_b128 v[188:191], v227 offset:51200
	ds_read_b128 v[192:195], v227 offset:52224
	ds_read_b128 v[196:199], v227 offset:53248
	ds_read_b128 v[200:203], v227 offset:54272
	ds_read_b128 v[204:207], v227 offset:55296
	ds_read_b128 v[208:211], v227 offset:56320
	s_add_u32 s100, s80, 0x80
	s_addc_u32 s101, s81, 0
	global_load_lds_dwordx4 v182, s[100:101]
	s_add_i32 m0, s0, 0x2000
	s_add_u32 s0, s80, 0x80080
	s_addc_u32 s1, s81, 0
	s_add_i32 s80, s86, s33
	global_load_lds_dwordx4 v176, s[100:101]
	s_mov_b32 m0, s80
	s_nop 0
	global_load_lds_dwordx4 v182, s[0:1]
	s_add_i32 m0, s80, 0x2000
	s_nop 0
	global_load_lds_dwordx4 v176, s[0:1]
	s_mov_b32 m0, s50
	s_nop 0
	s_add_u32 s100, s82, 0x80
	s_addc_u32 s101, s83, 0
	global_load_lds_dwordx4 v172, s[100:101]
	s_mov_b32 m0, s51
	s_nop 0
	global_load_lds_dwordx4 v174, s[100:101]
	s_waitcnt vmcnt(8)
	s_waitcnt lgkmcnt(0)
	s_setprio 1
	s_barrier
	v_mfma_f32_16x16x32_bf16 v[62:65], v[90:93], v[162:165], v[62:65]
	v_mfma_f32_16x16x32_bf16 v[58:61], v[98:101], v[162:165], v[58:61]
	v_mfma_f32_16x16x32_bf16 v[46:49], v[90:93], v[188:191], v[46:49]
	v_mfma_f32_16x16x32_bf16 v[42:45], v[98:101], v[188:191], v[42:45]
	v_mfma_f32_16x16x32_bf16 v[30:33], v[90:93], v[196:199], v[30:33]
	v_mfma_f32_16x16x32_bf16 v[26:29], v[98:101], v[196:199], v[26:29]
	v_mfma_f32_16x16x32_bf16 v[14:17], v[90:93], v[204:207], v[14:17]
	v_mfma_f32_16x16x32_bf16 v[10:13], v[98:101], v[204:207], v[10:13]
	v_mfma_f32_16x16x32_bf16 v[62:65], v[94:97], v[166:169], v[62:65]
	v_mfma_f32_16x16x32_bf16 v[58:61], v[102:105], v[166:169], v[58:61]
	v_mfma_f32_16x16x32_bf16 v[46:49], v[94:97], v[192:195], v[46:49]
	v_mfma_f32_16x16x32_bf16 v[42:45], v[102:105], v[192:195], v[42:45]
	v_mfma_f32_16x16x32_bf16 v[30:33], v[94:97], v[200:203], v[30:33]
	v_mfma_f32_16x16x32_bf16 v[26:29], v[102:105], v[200:203], v[26:29]
	v_mfma_f32_16x16x32_bf16 v[14:17], v[94:97], v[208:211], v[14:17]
	v_mfma_f32_16x16x32_bf16 v[10:13], v[102:105], v[208:211], v[10:13]
	v_mfma_f32_16x16x32_bf16 v[54:57], v[146:149], v[162:165], v[54:57]
	v_mfma_f32_16x16x32_bf16 v[50:53], v[154:157], v[162:165], v[50:53]
	v_mfma_f32_16x16x32_bf16 v[38:41], v[146:149], v[188:191], v[38:41]
	v_mfma_f32_16x16x32_bf16 v[34:37], v[154:157], v[188:191], v[34:37]
	v_mfma_f32_16x16x32_bf16 v[22:25], v[146:149], v[196:199], v[22:25]
	v_mfma_f32_16x16x32_bf16 v[18:21], v[154:157], v[196:199], v[18:21]
	v_mfma_f32_16x16x32_bf16 v[6:9], v[146:149], v[204:207], v[6:9]
	v_mfma_f32_16x16x32_bf16 v[2:5], v[154:157], v[204:207], v[2:5]
	v_mfma_f32_16x16x32_bf16 v[54:57], v[150:153], v[166:169], v[54:57]
	v_mfma_f32_16x16x32_bf16 v[50:53], v[158:161], v[166:169], v[50:53]
	v_mfma_f32_16x16x32_bf16 v[38:41], v[150:153], v[192:195], v[38:41]
	v_mfma_f32_16x16x32_bf16 v[34:37], v[158:161], v[192:195], v[34:37]
	v_mfma_f32_16x16x32_bf16 v[22:25], v[150:153], v[200:203], v[22:25]
	v_mfma_f32_16x16x32_bf16 v[18:21], v[158:161], v[200:203], v[18:21]
	v_mfma_f32_16x16x32_bf16 v[6:9], v[150:153], v[208:211], v[6:9]
	v_mfma_f32_16x16x32_bf16 v[2:5], v[158:161], v[208:211], v[2:5]
	s_barrier
	s_setprio 0
	s_add_i32 s84, s84, 2
	s_add_u32 s78, s78, 0x100
	s_addc_u32 s79, s79, 0
	s_add_u32 s75, s75, 0x100
	s_addc_u32 s77, s77, 0
	s_cmp_gt_u32 s84, 29
	s_cbranch_scc0 .LBB0_1170
	s_and_b64 vcc, exec, s[64:65]
	s_cbranch_vccz .LBB0_1173
	s_barrier

;     __host__ __device__ bool next(int i, Unit& u) const { const long L = (long)i * G + c; if (L >= lim) return false; unit_of((int)L, u); return true; }
;     __device__ __forceinline__ bool next(int i, Unit& v) const { if (i != 0) return false; v = u; return true; }
; #define PG8_STAGE(bufoff, gbase, voff) do { _Pragma("unroll") for (int _i = 0; _i < 2; ++_i) \
;         __builtin_amdgcn_global_load_lds((const unsigned*)((const char*)(gbase) + (voff)[_i]), (PG8_LAS unsigned*)(lds + (bufoff) + ldsw + _i * 8192), 16, 0, 0); } while (0)
; #define PG8_LDA(dst, b, h) do { _Pragma("unroll") for (int m = 0; m < 4; ++m) _Pragma("unroll") for (int k = 0; k < 2; ++k) dst[m][k] = *(const PG8_LAS bf16x8*)(lds + PG8_SA(b, h) + aoff + m * 2048 + k * 1024); } while (0)
;     ...
;         const bool has_next = S.next(ui + 1, nxt);
;         if constexpr (TP == 3) { if (ui > 0) tp_acc += __builtin_amdgcn_s_memrealtime() - tp3; }
;         const char* nA = has_next ? (const char*)g.A + (size_t)nxt.pm * tstep : cA; const char* nB = has_next ? (const char*)g.Bt + (size_t)nxt.pn * tstep : cB;
;         for (int t = 0; t < nt * KREP; t += 2) {
;             const bool last = (t == nt * KREP - 2);
;             const int t1w = KREP > 1 ? ((t + 1) & (nt - 1)) : t + 1, t2w = KREP > 1 ? ((t + 2) & (nt - 1)) : t + 2;
;             const char* a1 = cA + (size_t)t1w * kstep;
;             const char* a2 = last ? nA : cA + (size_t)t2w * kstep; const char* b2 = last ? nB : cB + (size_t)t2w * kstep;
;             const char* a3 = a2 + kstep; const char* b3 = b2 + kstep;
;             if (last && has_next) S.a_ready(nxt);
;             const int relax = __builtin_amdgcn_readfirstlane((MK_RELAXW && t == 0 && ui > 0) ? 1 : 0);
;             if constexpr (SP2) {
;             PG8_LDB(B0, 0, 0); PG8_LDB(B1, 0, 1); PG8_SCHED; PG8_LDA(At, 0, 0); PG8_STAGE(PG8_SA(1, 1), a1 + hstep, voffA);
;             PG8_WAIT_V_SEL(relax);
;             PG8_WAIT_L(0); PG8_BAR; PG8_MMA(0, 0, At, B0); PG8_MMA(0, 1, At, B1); PG8_BAR; PG8_SCHED;
;     ...
; #pragma unroll
;         for (int a = 0; a < 2; ++a)
; #pragma unroll
;             for (int b = 0; b < 2; ++b)
; #pragma unroll
;                 for (int m = 0; m < 4; ++m)
; #pragma unroll
;                     for (int n = 0; n < 2; ++n) acc[a][b][m][n] = (f32x4){0.f, 0.f, 0.f, 0.f};
;         cur = nxt; cA = nA; cB = nB; ++ui;
.LBB0_1326:
	s_ashr_i32 s89, s88, 31
	s_lshl_b64 s[40:41], s[88:89], 20
	s_add_u32 s90, s23, s40
	s_addc_u32 s91, s31, s41
	s_and_b64 s[40:41], s[8:9], exec
	s_cselect_b32 s59, s91, s13
	s_cselect_b32 s64, s90, s12
	s_ashr_i32 s87, s86, 31
	s_lshl_b64 s[40:41], s[86:87], 20
	s_add_u32 s92, s56, s40
	s_addc_u32 s93, s57, s41
	s_and_b64 s[40:41], s[8:9], exec
	s_cselect_b32 s65, s93, s97
	s_cselect_b32 s87, s92, s96
	s_add_u32 s66, s96, 0x100
	v_mov_b64_e32 v[2:3], 0
	v_mov_b64_e32 v[4:5], 0
	v_mov_b64_e32 v[6:7], 0
	v_mov_b64_e32 v[8:9], 0
	v_mov_b64_e32 v[10:11], 0
	v_mov_b64_e32 v[12:13], 0
	v_mov_b64_e32 v[14:15], 0
	v_mov_b64_e32 v[16:17], 0
	v_mov_b64_e32 v[18:19], 0
	v_mov_b64_e32 v[20:21], 0
	v_mov_b64_e32 v[22:23], 0
	v_mov_b64_e32 v[24:25], 0
	v_mov_b64_e32 v[26:27], 0
	v_mov_b64_e32 v[28:29], 0
	v_mov_b64_e32 v[30:31], 0
	v_mov_b64_e32 v[32:33], 0
	v_mov_b64_e32 v[34:35], 0
	v_mov_b64_e32 v[36:37], 0
	v_mov_b64_e32 v[38:39], 0
	v_mov_b64_e32 v[40:41], 0
	v_mov_b64_e32 v[42:43], 0
	v_mov_b64_e32 v[44:45], 0
	v_mov_b64_e32 v[46:47], 0
	v_mov_b64_e32 v[48:49], 0
	v_mov_b64_e32 v[50:51], 0
	v_mov_b64_e32 v[52:53], 0
	v_mov_b64_e32 v[54:55], 0
	v_mov_b64_e32 v[56:57], 0
	v_mov_b64_e32 v[58:59], 0
	v_mov_b64_e32 v[60:61], 0
	v_mov_b64_e32 v[62:63], 0
	v_mov_b64_e32 v[64:65], 0
	v_mov_b64_e32 v[74:75], 0
	v_mov_b64_e32 v[76:77], 0
	v_mov_b64_e32 v[78:79], 0
	v_mov_b64_e32 v[80:81], 0
	v_mov_b64_e32 v[86:87], 0
	v_mov_b64_e32 v[88:89], 0
	v_mov_b64_e32 v[90:91], 0
	v_mov_b64_e32 v[92:93], 0
	v_mov_b64_e32 v[94:95], 0
	v_mov_b64_e32 v[96:97], 0
	v_mov_b64_e32 v[98:99], 0
	v_mov_b64_e32 v[100:101], 0
	v_mov_b64_e32 v[102:103], 0
	v_mov_b64_e32 v[104:105], 0
	v_mov_b64_e32 v[106:107], 0
	v_mov_b64_e32 v[108:109], 0
	v_mov_b64_e32 v[110:111], 0
	v_mov_b64_e32 v[112:113], 0
	v_mov_b64_e32 v[114:115], 0
	v_mov_b64_e32 v[116:117], 0
	v_mov_b64_e32 v[118:119], 0
	v_mov_b64_e32 v[120:121], 0
	v_mov_b64_e32 v[122:123], 0
	v_mov_b64_e32 v[124:125], 0
	v_mov_b64_e32 v[126:127], 0
	v_mov_b64_e32 v[128:129], 0
	v_mov_b64_e32 v[130:131], 0
	v_mov_b64_e32 v[132:133], 0
	v_mov_b64_e32 v[134:135], 0
	v_mov_b64_e32 v[136:137], 0
	v_mov_b64_e32 v[138:139], 0
	v_mov_b64_e32 v[140:141], 0
	s_addc_u32 s67, s97, 0
	s_mov_b32 s0, -2
	v_add_u32_e32 v200, 0x10000, v203
.LBB0_1327:
	s_add_u32 s96, s12, 0x100
	s_addc_u32 s97, s13, 0
	s_add_i32 s51, 0, 0x10000
	s_cmp_eq_u32 s0, 28
	s_cselect_b32 s41, s59, s97
	s_cselect_b32 s40, s64, s96
	s_cselect_b32 vcc_hi, s65, s67
	s_cselect_b32 vcc_lo, s87, s66
	s_add_i32 s19, 0, 0x14000
	ds_read_b128 v[66:69], v200
	ds_read_b128 v[70:73], v200 offset:1024
	ds_read_b128 v[82:85], v200 offset:2048
	ds_read_b128 v[142:145], v200 offset:3072
	ds_read_b128 v[146:149], v200 offset:16384
	ds_read_b128 v[150:153], v200 offset:17408
	ds_read_b128 v[154:157], v200 offset:18432
	ds_read_b128 v[158:161], v200 offset:19456
	s_add_i32 m0, s95, 0xc000
	ds_read_b128 v[162:165], v219
	ds_read_b128 v[166:169], v219 offset:1024
	ds_read_b128 v[170:173], v219 offset:2048
	ds_read_b128 v[174:177], v219 offset:3072
	ds_read_b128 v[178:181], v219 offset:4096
	ds_read_b128 v[184:187], v219 offset:5120
	ds_read_b128 v[220:223], v219 offset:6144
	ds_read_b128 v[224:227], v219 offset:7168
	global_load_lds_dwordx4 v196, s[12:13]
	s_add_i32 m0, s95, 0xe000
	s_nop 0
	global_load_lds_dwordx4 v198, s[12:13]
	s_waitcnt vmcnt(8)
	s_waitcnt lgkmcnt(0)
	s_setprio 1
	s_barrier
	v_mfma_f32_16x16x32_bf16 v[114:117], v[66:69], v[162:165], v[114:117]
	v_mfma_f32_16x16x32_bf16 v[106:109], v[82:85], v[162:165], v[106:109]
	v_mfma_f32_16x16x32_bf16 v[110:113], v[66:69], v[170:173], v[110:113]
	v_mfma_f32_16x16x32_bf16 v[102:105], v[82:85], v[170:173], v[102:105]
	v_mfma_f32_16x16x32_bf16 v[78:81], v[66:69], v[178:181], v[78:81]
	v_mfma_f32_16x16x32_bf16 v[138:141], v[82:85], v[178:181], v[138:141]
	v_mfma_f32_16x16x32_bf16 v[74:77], v[66:69], v[220:223], v[74:77]
	v_mfma_f32_16x16x32_bf16 v[134:137], v[82:85], v[220:223], v[134:137]
	v_mfma_f32_16x16x32_bf16 v[114:117], v[70:73], v[166:169], v[114:117]
	v_mfma_f32_16x16x32_bf16 v[106:109], v[142:145], v[166:169], v[106:109]
	v_mfma_f32_16x16x32_bf16 v[110:113], v[70:73], v[174:177], v[110:113]
	v_mfma_f32_16x16x32_bf16 v[102:105], v[142:145], v[174:177], v[102:105]
	v_mfma_f32_16x16x32_bf16 v[78:81], v[70:73], v[184:187], v[78:81]
	v_mfma_f32_16x16x32_bf16 v[138:141], v[142:145], v[184:187], v[138:141]
	v_mfma_f32_16x16x32_bf16 v[74:77], v[70:73], v[224:227], v[74:77]
	v_mfma_f32_16x16x32_bf16 v[134:137], v[142:145], v[224:227], v[134:137]
	v_mfma_f32_16x16x32_bf16 v[98:101], v[146:149], v[162:165], v[98:101]
	v_mfma_f32_16x16x32_bf16 v[90:93], v[154:157], v[162:165], v[90:93]
	v_mfma_f32_16x16x32_bf16 v[94:97], v[146:149], v[170:173], v[94:97]
	v_mfma_f32_16x16x32_bf16 v[86:89], v[154:157], v[170:173], v[86:89]
	v_mfma_f32_16x16x32_bf16 v[130:133], v[146:149], v[178:181], v[130:133]
	v_mfma_f32_16x16x32_bf16 v[122:125], v[154:157], v[178:181], v[122:125]
	v_mfma_f32_16x16x32_bf16 v[126:129], v[146:149], v[220:223], v[126:129]
	v_mfma_f32_16x16x32_bf16 v[118:121], v[154:157], v[220:223], v[118:121]
	v_mfma_f32_16x16x32_bf16 v[98:101], v[150:153], v[166:169], v[98:101]
	v_mfma_f32_16x16x32_bf16 v[90:93], v[158:161], v[166:169], v[90:93]
	v_mfma_f32_16x16x32_bf16 v[94:97], v[150:153], v[174:177], v[94:97]
	v_mfma_f32_16x16x32_bf16 v[86:89], v[158:161], v[174:177], v[86:89]
	v_mfma_f32_16x16x32_bf16 v[130:133], v[150:153], v[184:187], v[130:133]
	v_mfma_f32_16x16x32_bf16 v[122:125], v[158:161], v[184:187], v[122:125]
	v_mfma_f32_16x16x32_bf16 v[126:129], v[150:153], v[224:227], v[126:129]
	v_mfma_f32_16x16x32_bf16 v[118:121], v[158:161], v[224:227], v[118:121]
	s_barrier
; #define PG8_STAGE(bufoff, gbase, voff) do { _Pragma("unroll") for (int _i = 0; _i < 2; ++_i) \
;         __builtin_amdgcn_global_load_lds((const unsigned*)((const char*)(gbase) + (voff)[_i]), (PG8_LAS unsigned*)(lds + (bufoff) + ldsw + _i * 8192), 16, 0, 0); } while (0)
; #define PG8_LDA(dst, b, h) do { _Pragma("unroll") for (int m = 0; m < 4; ++m) _Pragma("unroll") for (int k = 0; k < 2; ++k) dst[m][k] = *(const PG8_LAS bf16x8*)(lds + PG8_SA(b, h) + aoff + m * 2048 + k * 1024); } while (0)
; #define PG8_LDB(dst, b, h) do { _Pragma("unroll") for (int n = 0; n < 2; ++n) _Pragma("unroll") for (int k = 0; k < 2; ++k) dst[n][k] = *(const PG8_LAS bf16x8*)(lds + PG8_SB(b, h) + boff + n * 2048 + k * 1024); } while (0)
; #define PG8_WAIT_V(n) asm volatile("s_waitcnt vmcnt(" #n ")" ::: "memory")
; #define PG8_WAIT_L(n) asm volatile("s_waitcnt lgkmcnt(" #n ")" ::: "memory")
; #define PG8_WAIT_V_SEL(sel) asm volatile("s_cmp_eq_u32 %0, 0\n\ts_cbranch_scc1 .Lw8_%=\n\ts_waitcnt vmcnt(22)\n\ts_branch .Lwd_%=\n.Lw8_%=:\n\ts_waitcnt vmcnt(8)\n.Lwd_%=:" :: "s"(sel) : "memory", "scc")
; #define PG8_BAR __builtin_amdgcn_s_barrier()
; #define PG8_SCHED __builtin_amdgcn_sched_barrier(0)
;     ...
;             PG8_LDA(At, 0, 1); PG8_STAGE(PG8_SB(0, 0), b2, voffB); PG8_STAGE(PG8_SB(0, 1), b2 + hstep, voffB); PG8_STAGE(PG8_SA(0, 0), a2, voffA);
;             PG8_WAIT_V_SEL(relax);
;             PG8_WAIT_L(0); PG8_BAR; PG8_MMA(1, 0, At, B0); PG8_MMA(1, 1, At, B1); PG8_BAR; PG8_SCHED;
;             PG8_LDB(B0, 1, 0); PG8_LDB(B1, 1, 1); PG8_SCHED; PG8_LDA(At, 1, 0); PG8_STAGE(PG8_SA(0, 1), a2 + hstep, voffA);
;             PG8_WAIT_V(8); PG8_WAIT_L(0); PG8_BAR; PG8_MMA(0, 0, At, B0); PG8_MMA(0, 1, At, B1); PG8_BAR; PG8_SCHED;
	s_setprio 0
	s_add_i32 s12, s51, s37
	s_mov_b32 m0, s12
	ds_read_b128 v[162:165], v219 offset:16384
	ds_read_b128 v[166:169], v219 offset:17408
	ds_read_b128 v[170:173], v219 offset:18432
	ds_read_b128 v[174:177], v219 offset:19456
	ds_read_b128 v[178:181], v219 offset:20480
	ds_read_b128 v[184:187], v219 offset:21504
	ds_read_b128 v[220:223], v219 offset:22528
	ds_read_b128 v[224:227], v219 offset:23552
	global_load_lds_dwordx4 v182, vcc
	s_add_i32 m0, s12, 0x2000
	s_add_u32 s12, vcc_lo, 0x80000
	s_addc_u32 s13, vcc_hi, 0
	s_add_i32 s19, s19, s37
	global_load_lds_dwordx4 v192, vcc
	s_mov_b32 m0, s19
	s_nop 0
	global_load_lds_dwordx4 v182, s[12:13]
	s_add_i32 m0, s19, 0x2000
	s_nop 0
	global_load_lds_dwordx4 v192, s[12:13]
	s_mov_b32 m0, s95
	s_nop 0
	global_load_lds_dwordx4 v188, s[40:41]
	s_mov_b32 m0, s20
	s_nop 0
	global_load_lds_dwordx4 v190, s[40:41]
	s_waitcnt vmcnt(8)
	s_waitcnt lgkmcnt(0)
	s_setprio 1
	s_barrier
	v_mfma_f32_16x16x32_bf16 v[30:33], v[66:69], v[162:165], v[30:33]
	v_mfma_f32_16x16x32_bf16 v[22:25], v[82:85], v[162:165], v[22:25]
	v_mfma_f32_16x16x32_bf16 v[26:29], v[66:69], v[170:173], v[26:29]
	v_mfma_f32_16x16x32_bf16 v[18:21], v[82:85], v[170:173], v[18:21]
	v_mfma_f32_16x16x32_bf16 v[62:65], v[66:69], v[178:181], v[62:65]
	v_mfma_f32_16x16x32_bf16 v[54:57], v[82:85], v[178:181], v[54:57]
	v_mfma_f32_16x16x32_bf16 v[58:61], v[66:69], v[220:223], v[58:61]
	v_mfma_f32_16x16x32_bf16 v[50:53], v[82:85], v[220:223], v[50:53]
	v_mfma_f32_16x16x32_bf16 v[30:33], v[70:73], v[166:169], v[30:33]
	v_mfma_f32_16x16x32_bf16 v[22:25], v[142:145], v[166:169], v[22:25]
	v_mfma_f32_16x16x32_bf16 v[26:29], v[70:73], v[174:177], v[26:29]
	v_mfma_f32_16x16x32_bf16 v[18:21], v[142:145], v[174:177], v[18:21]
	v_mfma_f32_16x16x32_bf16 v[62:65], v[70:73], v[184:187], v[62:65]
	v_mfma_f32_16x16x32_bf16 v[54:57], v[142:145], v[184:187], v[54:57]
	v_mfma_f32_16x16x32_bf16 v[58:61], v[70:73], v[224:227], v[58:61]
	v_mfma_f32_16x16x32_bf16 v[50:53], v[142:145], v[224:227], v[50:53]
	v_mfma_f32_16x16x32_bf16 v[14:17], v[146:149], v[162:165], v[14:17]
	v_mfma_f32_16x16x32_bf16 v[6:9], v[154:157], v[162:165], v[6:9]
	v_mfma_f32_16x16x32_bf16 v[10:13], v[146:149], v[170:173], v[10:13]
	v_mfma_f32_16x16x32_bf16 v[2:5], v[154:157], v[170:173], v[2:5]
	v_mfma_f32_16x16x32_bf16 v[46:49], v[146:149], v[178:181], v[46:49]
	v_mfma_f32_16x16x32_bf16 v[34:37], v[154:157], v[178:181], v[34:37]
	v_mfma_f32_16x16x32_bf16 v[38:41], v[146:149], v[220:223], v[38:41]
	v_mfma_f32_16x16x32_bf16 v[42:45], v[154:157], v[220:223], v[42:45]
	v_mfma_f32_16x16x32_bf16 v[14:17], v[150:153], v[166:169], v[14:17]
	v_mfma_f32_16x16x32_bf16 v[6:9], v[158:161], v[166:169], v[6:9]
	v_mfma_f32_16x16x32_bf16 v[10:13], v[150:153], v[174:177], v[10:13]
	v_mfma_f32_16x16x32_bf16 v[2:5], v[158:161], v[174:177], v[2:5]
	v_mfma_f32_16x16x32_bf16 v[46:49], v[150:153], v[184:187], v[46:49]
	v_mfma_f32_16x16x32_bf16 v[34:37], v[158:161], v[184:187], v[34:37]
	v_mfma_f32_16x16x32_bf16 v[38:41], v[150:153], v[224:227], v[38:41]
	v_mfma_f32_16x16x32_bf16 v[42:45], v[158:161], v[224:227], v[42:45]
	s_barrier
	s_setprio 0
	s_add_i32 s19, 0, 0x18000
	s_add_i32 s51, 0, 0x1c000
	ds_read_b128 v[66:69], v200 offset:32768
	ds_read_b128 v[70:73], v200 offset:33792
	ds_read_b128 v[82:85], v200 offset:34816
	ds_read_b128 v[142:145], v200 offset:35840
	ds_read_b128 v[146:149], v200 offset:49152
	ds_read_b128 v[150:153], v200 offset:50176
	ds_read_b128 v[154:157], v200 offset:51200
	ds_read_b128 v[158:161], v200 offset:52224
	s_add_u32 s12, s40, 0x80000
	s_addc_u32 s13, s41, 0
	s_mov_b32 m0, s44
	ds_read_b128 v[162:165], v219 offset:32768
	ds_read_b128 v[166:169], v219 offset:33792
	ds_read_b128 v[170:173], v219 offset:34816
	ds_read_b128 v[174:177], v219 offset:35840
	ds_read_b128 v[178:181], v219 offset:36864
	ds_read_b128 v[184:187], v219 offset:37888
	ds_read_b128 v[220:223], v219 offset:38912
	ds_read_b128 v[224:227], v219 offset:39936
	global_load_lds_dwordx4 v188, s[12:13]
	s_mov_b32 m0, s46
	s_nop 0
	global_load_lds_dwordx4 v190, s[12:13]
	s_waitcnt vmcnt(8)
	s_waitcnt lgkmcnt(0)
	s_setprio 1
	s_barrier
; #define PG8_STAGE(bufoff, gbase, voff) do { _Pragma("unroll") for (int _i = 0; _i < 2; ++_i) \
;         __builtin_amdgcn_global_load_lds((const unsigned*)((const char*)(gbase) + (voff)[_i]), (PG8_LAS unsigned*)(lds + (bufoff) + ldsw + _i * 8192), 16, 0, 0); } while (0)
; #define PG8_LDA(dst, b, h) do { _Pragma("unroll") for (int m = 0; m < 4; ++m) _Pragma("unroll") for (int k = 0; k < 2; ++k) dst[m][k] = *(const PG8_LAS bf16x8*)(lds + PG8_SA(b, h) + aoff + m * 2048 + k * 1024); } while (0)
; #define PG8_WAIT_V(n) asm volatile("s_waitcnt vmcnt(" #n ")" ::: "memory")
; #define PG8_WAIT_L(n) asm volatile("s_waitcnt lgkmcnt(" #n ")" ::: "memory")
; #define PG8_BAR __builtin_amdgcn_s_barrier()
; #define PG8_SCHED __builtin_amdgcn_sched_barrier(0)
;     ...
;             PG8_WAIT_V(8); PG8_WAIT_L(0); PG8_BAR; PG8_MMA(0, 0, At, B0); PG8_MMA(0, 1, At, B1); PG8_BAR; PG8_SCHED;
;             PG8_LDA(At, 1, 1); PG8_STAGE(PG8_SB(1, 0), b3, voffB); PG8_STAGE(PG8_SB(1, 1), b3 + hstep, voffB); PG8_STAGE(PG8_SA(1, 0), a3, voffA);
;             PG8_WAIT_V(8); PG8_WAIT_L(0); PG8_BAR; PG8_MMA(1, 0, At, B0); PG8_MMA(1, 1, At, B1); PG8_BAR; PG8_SCHED;
	v_mfma_f32_16x16x32_bf16 v[114:117], v[66:69], v[162:165], v[114:117]
	v_mfma_f32_16x16x32_bf16 v[106:109], v[82:85], v[162:165], v[106:109]
	v_mfma_f32_16x16x32_bf16 v[110:113], v[66:69], v[170:173], v[110:113]
	v_mfma_f32_16x16x32_bf16 v[102:105], v[82:85], v[170:173], v[102:105]
	v_mfma_f32_16x16x32_bf16 v[78:81], v[66:69], v[178:181], v[78:81]
	v_mfma_f32_16x16x32_bf16 v[138:141], v[82:85], v[178:181], v[138:141]
	v_mfma_f32_16x16x32_bf16 v[74:77], v[66:69], v[220:223], v[74:77]
	v_mfma_f32_16x16x32_bf16 v[134:137], v[82:85], v[220:223], v[134:137]
	v_mfma_f32_16x16x32_bf16 v[114:117], v[70:73], v[166:169], v[114:117]
	v_mfma_f32_16x16x32_bf16 v[106:109], v[142:145], v[166:169], v[106:109]
	v_mfma_f32_16x16x32_bf16 v[110:113], v[70:73], v[174:177], v[110:113]
	v_mfma_f32_16x16x32_bf16 v[102:105], v[142:145], v[174:177], v[102:105]
	v_mfma_f32_16x16x32_bf16 v[78:81], v[70:73], v[184:187], v[78:81]
	v_mfma_f32_16x16x32_bf16 v[138:141], v[142:145], v[184:187], v[138:141]
	v_mfma_f32_16x16x32_bf16 v[74:77], v[70:73], v[224:227], v[74:77]
	v_mfma_f32_16x16x32_bf16 v[134:137], v[142:145], v[224:227], v[134:137]
	v_mfma_f32_16x16x32_bf16 v[98:101], v[146:149], v[162:165], v[98:101]
	v_mfma_f32_16x16x32_bf16 v[90:93], v[154:157], v[162:165], v[90:93]
	v_mfma_f32_16x16x32_bf16 v[94:97], v[146:149], v[170:173], v[94:97]
	v_mfma_f32_16x16x32_bf16 v[86:89], v[154:157], v[170:173], v[86:89]
	v_mfma_f32_16x16x32_bf16 v[130:133], v[146:149], v[178:181], v[130:133]
	v_mfma_f32_16x16x32_bf16 v[122:125], v[154:157], v[178:181], v[122:125]
	v_mfma_f32_16x16x32_bf16 v[126:129], v[146:149], v[220:223], v[126:129]
	v_mfma_f32_16x16x32_bf16 v[118:121], v[154:157], v[220:223], v[118:121]
	v_mfma_f32_16x16x32_bf16 v[98:101], v[150:153], v[166:169], v[98:101]
	v_mfma_f32_16x16x32_bf16 v[90:93], v[158:161], v[166:169], v[90:93]
	v_mfma_f32_16x16x32_bf16 v[94:97], v[150:153], v[174:177], v[94:97]
	v_mfma_f32_16x16x32_bf16 v[86:89], v[158:161], v[174:177], v[86:89]
	v_mfma_f32_16x16x32_bf16 v[130:133], v[150:153], v[184:187], v[130:133]
	v_mfma_f32_16x16x32_bf16 v[122:125], v[158:161], v[184:187], v[122:125]
	v_mfma_f32_16x16x32_bf16 v[126:129], v[150:153], v[224:227], v[126:129]
	v_mfma_f32_16x16x32_bf16 v[118:121], v[158:161], v[224:227], v[118:121]
	s_barrier
	s_setprio 0
	s_add_i32 s12, s19, s37
	s_mov_b32 m0, s12
	ds_read_b128 v[162:165], v219 offset:49152
	ds_read_b128 v[166:169], v219 offset:50176
	ds_read_b128 v[170:173], v219 offset:51200
	ds_read_b128 v[174:177], v219 offset:52224
	ds_read_b128 v[178:181], v219 offset:53248
	ds_read_b128 v[184:187], v219 offset:54272
	ds_read_b128 v[220:223], v219 offset:55296
	ds_read_b128 v[224:227], v219 offset:56320
	s_add_u32 s100, vcc_lo, 0x80
	s_addc_u32 s101, vcc_hi, 0
	global_load_lds_dwordx4 v182, s[100:101]
	s_add_i32 m0, s12, 0x2000
	s_add_u32 s12, vcc_lo, 0x80080
	s_addc_u32 s13, vcc_hi, 0
	s_add_i32 s19, s51, s37
	global_load_lds_dwordx4 v192, s[100:101]
	s_mov_b32 m0, s19
	s_nop 0
	global_load_lds_dwordx4 v182, s[12:13]
	s_add_i32 m0, s19, 0x2000
	s_nop 0
	global_load_lds_dwordx4 v192, s[12:13]
	s_mov_b32 m0, s45
	s_nop 0
	s_add_u32 s100, s40, 0x80
	s_addc_u32 s101, s41, 0
	global_load_lds_dwordx4 v188, s[100:101]
	s_mov_b32 m0, s24
	s_nop 0
	global_load_lds_dwordx4 v190, s[100:101]
	s_waitcnt vmcnt(8)
	s_waitcnt lgkmcnt(0)
	s_setprio 1
	s_barrier
	v_mfma_f32_16x16x32_bf16 v[30:33], v[66:69], v[162:165], v[30:33]
	v_mfma_f32_16x16x32_bf16 v[22:25], v[82:85], v[162:165], v[22:25]
	v_mfma_f32_16x16x32_bf16 v[26:29], v[66:69], v[170:173], v[26:29]
	v_mfma_f32_16x16x32_bf16 v[18:21], v[82:85], v[170:173], v[18:21]
	v_mfma_f32_16x16x32_bf16 v[62:65], v[66:69], v[178:181], v[62:65]
	v_mfma_f32_16x16x32_bf16 v[54:57], v[82:85], v[178:181], v[54:57]
	v_mfma_f32_16x16x32_bf16 v[58:61], v[66:69], v[220:223], v[58:61]
	v_mfma_f32_16x16x32_bf16 v[50:53], v[82:85], v[220:223], v[50:53]
	v_mfma_f32_16x16x32_bf16 v[30:33], v[70:73], v[166:169], v[30:33]
	v_mfma_f32_16x16x32_bf16 v[22:25], v[142:145], v[166:169], v[22:25]
	v_mfma_f32_16x16x32_bf16 v[26:29], v[70:73], v[174:177], v[26:29]
	v_mfma_f32_16x16x32_bf16 v[18:21], v[142:145], v[174:177], v[18:21]
	v_mfma_f32_16x16x32_bf16 v[62:65], v[70:73], v[184:187], v[62:65]
	v_mfma_f32_16x16x32_bf16 v[54:57], v[142:145], v[184:187], v[54:57]
	v_mfma_f32_16x16x32_bf16 v[58:61], v[70:73], v[224:227], v[58:61]
	v_mfma_f32_16x16x32_bf16 v[50:53], v[142:145], v[224:227], v[50:53]
	v_mfma_f32_16x16x32_bf16 v[14:17], v[146:149], v[162:165], v[14:17]
	v_mfma_f32_16x16x32_bf16 v[6:9], v[154:157], v[162:165], v[6:9]
	v_mfma_f32_16x16x32_bf16 v[10:13], v[146:149], v[170:173], v[10:13]
	v_mfma_f32_16x16x32_bf16 v[2:5], v[154:157], v[170:173], v[2:5]
	v_mfma_f32_16x16x32_bf16 v[46:49], v[146:149], v[178:181], v[46:49]
	v_mfma_f32_16x16x32_bf16 v[34:37], v[154:157], v[178:181], v[34:37]
	v_mfma_f32_16x16x32_bf16 v[38:41], v[146:149], v[220:223], v[38:41]
	v_mfma_f32_16x16x32_bf16 v[42:45], v[154:157], v[220:223], v[42:45]
	v_mfma_f32_16x16x32_bf16 v[14:17], v[150:153], v[166:169], v[14:17]
	v_mfma_f32_16x16x32_bf16 v[6:9], v[158:161], v[166:169], v[6:9]
	v_mfma_f32_16x16x32_bf16 v[10:13], v[150:153], v[174:177], v[10:13]
	v_mfma_f32_16x16x32_bf16 v[2:5], v[158:161], v[174:177], v[2:5]
	v_mfma_f32_16x16x32_bf16 v[46:49], v[150:153], v[184:187], v[46:49]
	v_mfma_f32_16x16x32_bf16 v[34:37], v[158:161], v[184:187], v[34:37]
	v_mfma_f32_16x16x32_bf16 v[38:41], v[150:153], v[224:227], v[38:41]
	v_mfma_f32_16x16x32_bf16 v[42:45], v[158:161], v[224:227], v[42:45]
	s_barrier
	s_setprio 0
	s_add_i32 s0, s0, 2
	s_add_u32 s66, s66, 0x100
	s_addc_u32 s67, s67, 0
	s_cmp_gt_u32 s0, 29
	s_mov_b64 s[12:13], s[96:97]
	s_cbranch_scc0 .LBB0_1327
	s_and_b64 vcc, exec, s[78:79]
	s_cbranch_vccz .LBB0_1330
	s_barrier

;     __host__ __device__ bool next(int i, Unit& u) const { const long L = (long)i * G + c; if (L >= lim) return false; unit_of((int)L, u); return true; }
;     __device__ __forceinline__ bool next(int i, Unit& v) const { if (i != 0) return false; v = u; return true; }
; #define PG8_STAGE(bufoff, gbase, voff) do { _Pragma("unroll") for (int _i = 0; _i < 2; ++_i) \
;         __builtin_amdgcn_global_load_lds((const unsigned*)((const char*)(gbase) + (voff)[_i]), (PG8_LAS unsigned*)(lds + (bufoff) + ldsw + _i * 8192), 16, 0, 0); } while (0)
; #define PG8_LDA(dst, b, h) do { _Pragma("unroll") for (int m = 0; m < 4; ++m) _Pragma("unroll") for (int k = 0; k < 2; ++k) dst[m][k] = *(const PG8_LAS bf16x8*)(lds + PG8_SA(b, h) + aoff + m * 2048 + k * 1024); } while (0)
;     ...
;         const bool has_next = S.next(ui + 1, nxt);
;         if constexpr (TP == 3) { if (ui > 0) tp_acc += __builtin_amdgcn_s_memrealtime() - tp3; }
;         const char* nA = has_next ? (const char*)g.A + (size_t)nxt.pm * tstep : cA; const char* nB = has_next ? (const char*)g.Bt + (size_t)nxt.pn * tstep : cB;
;         for (int t = 0; t < nt * KREP; t += 2) {
;             const bool last = (t == nt * KREP - 2);
;             const int t1w = KREP > 1 ? ((t + 1) & (nt - 1)) : t + 1, t2w = KREP > 1 ? ((t + 2) & (nt - 1)) : t + 2;
;             const char* a1 = cA + (size_t)t1w * kstep;
;             const char* a2 = last ? nA : cA + (size_t)t2w * kstep; const char* b2 = last ? nB : cB + (size_t)t2w * kstep;
;             const char* a3 = a2 + kstep; const char* b3 = b2 + kstep;
;             if (last && has_next) S.a_ready(nxt);
;             const int relax = __builtin_amdgcn_readfirstlane((MK_RELAXW && t == 0 && ui > 0) ? 1 : 0);
;             if constexpr (SP2) {
;             PG8_LDB(B0, 0, 0); PG8_LDB(B1, 0, 1); PG8_SCHED; PG8_LDA(At, 0, 0); PG8_STAGE(PG8_SA(1, 1), a1 + hstep, voffA);
;             PG8_WAIT_V_SEL(relax);
;             PG8_WAIT_L(0); PG8_BAR; PG8_MMA(0, 0, At, B0); PG8_MMA(0, 1, At, B1); PG8_BAR; PG8_SCHED;
;     ...
; #pragma unroll
;         for (int a = 0; a < 2; ++a)
; #pragma unroll
;             for (int b = 0; b < 2; ++b)
; #pragma unroll
;                 for (int m = 0; m < 4; ++m)
; #pragma unroll
;                     for (int n = 0; n < 2; ++n) acc[a][b][m][n] = (f32x4){0.f, 0.f, 0.f, 0.f};
;         cur = nxt; cA = nA; cB = nB; ++ui;
.LBB0_1647:
	s_add_u32 s37, s10, 0x100
	v_mov_b64_e32 v[2:3], 0
	v_mov_b64_e32 v[4:5], 0
	v_mov_b64_e32 v[6:7], 0
	v_mov_b64_e32 v[8:9], 0
	v_mov_b64_e32 v[10:11], 0
	v_mov_b64_e32 v[12:13], 0
	v_mov_b64_e32 v[14:15], 0
	v_mov_b64_e32 v[16:17], 0
	v_mov_b64_e32 v[18:19], 0
	v_mov_b64_e32 v[20:21], 0
	v_mov_b64_e32 v[22:23], 0
	v_mov_b64_e32 v[24:25], 0
	v_mov_b64_e32 v[26:27], 0
	v_mov_b64_e32 v[28:29], 0
	v_mov_b64_e32 v[30:31], 0
	v_mov_b64_e32 v[32:33], 0
	v_mov_b64_e32 v[34:35], 0
	v_mov_b64_e32 v[36:37], 0
	v_mov_b64_e32 v[38:39], 0
	v_mov_b64_e32 v[40:41], 0
	v_mov_b64_e32 v[42:43], 0
	v_mov_b64_e32 v[44:45], 0
	v_mov_b64_e32 v[46:47], 0
	v_mov_b64_e32 v[48:49], 0
	v_mov_b64_e32 v[50:51], 0
	v_mov_b64_e32 v[52:53], 0
	v_mov_b64_e32 v[54:55], 0
	v_mov_b64_e32 v[56:57], 0
	v_mov_b64_e32 v[66:67], 0
	v_mov_b64_e32 v[68:69], 0
	v_mov_b64_e32 v[70:71], 0
	v_mov_b64_e32 v[72:73], 0
	v_mov_b64_e32 v[82:83], 0
	v_mov_b64_e32 v[84:85], 0
	v_mov_b64_e32 v[86:87], 0
	v_mov_b64_e32 v[88:89], 0
	v_mov_b64_e32 v[90:91], 0
	v_mov_b64_e32 v[92:93], 0
	v_mov_b64_e32 v[94:95], 0
	v_mov_b64_e32 v[96:97], 0
	v_mov_b64_e32 v[98:99], 0
	v_mov_b64_e32 v[100:101], 0
	v_mov_b64_e32 v[102:103], 0
	v_mov_b64_e32 v[104:105], 0
	v_mov_b64_e32 v[106:107], 0
	v_mov_b64_e32 v[108:109], 0
	v_mov_b64_e32 v[110:111], 0
	v_mov_b64_e32 v[112:113], 0
	v_mov_b64_e32 v[114:115], 0
	v_mov_b64_e32 v[116:117], 0
	v_mov_b64_e32 v[118:119], 0
	v_mov_b64_e32 v[120:121], 0
	v_mov_b64_e32 v[122:123], 0
	v_mov_b64_e32 v[124:125], 0
	v_mov_b64_e32 v[126:127], 0
	v_mov_b64_e32 v[128:129], 0
	v_mov_b64_e32 v[134:135], 0
	v_mov_b64_e32 v[136:137], 0
	v_mov_b64_e32 v[138:139], 0
	v_mov_b64_e32 v[140:141], 0
	v_mov_b64_e32 v[146:147], 0
	v_mov_b64_e32 v[148:149], 0
	v_mov_b64_e32 v[150:151], 0
	v_mov_b64_e32 v[152:153], 0
	s_addc_u32 s44, s11, 0
	s_mov_b32 s45, -2
	s_waitcnt lgkmcnt(0)
	v_add_u32_e32 v206, 0x10000, v243
.LBB0_1648:
	s_add_u32 s10, s8, 0x100
	s_addc_u32 s11, s9, 0
	s_add_i32 s46, 0, 0x10000
	s_cmpk_eq_i32 s45, 0x52
	s_cselect_b32 s41, s1, s11
	s_cselect_b32 s40, s0, s10
	s_cselect_b32 s81, s79, s44
	s_cselect_b32 s80, s78, s37
	s_add_i32 s47, 0, 0x14000
	ds_read_b128 v[58:61], v206
	ds_read_b128 v[62:65], v206 offset:1024
	ds_read_b128 v[74:77], v206 offset:2048
	ds_read_b128 v[78:81], v206 offset:3072
	ds_read_b128 v[130:133], v206 offset:16384
	ds_read_b128 v[142:145], v206 offset:17408
	ds_read_b128 v[154:157], v206 offset:18432
	ds_read_b128 v[158:161], v206 offset:19456
	s_add_i32 m0, s91, 0xc000
	ds_read_b128 v[162:165], v246
	ds_read_b128 v[166:169], v246 offset:1024
	ds_read_b128 v[170:173], v246 offset:2048
	ds_read_b128 v[174:177], v246 offset:3072
	ds_read_b128 v[184:187], v246 offset:4096
	ds_read_b128 v[194:197], v246 offset:5120
	ds_read_b128 v[198:201], v246 offset:6144
	ds_read_b128 v[202:205], v246 offset:7168
	global_load_lds_dwordx4 v190, s[8:9]
	s_add_i32 m0, s91, 0xe000
	s_nop 0
	global_load_lds_dwordx4 v192, s[8:9]
	s_waitcnt vmcnt(8)
	s_waitcnt lgkmcnt(0)
	s_setprio 1
	s_barrier
	v_mfma_f32_16x16x32_bf16 v[150:153], v[58:61], v[162:165], v[150:153]
	v_mfma_f32_16x16x32_bf16 v[146:149], v[74:77], v[162:165], v[146:149]
	v_mfma_f32_16x16x32_bf16 v[126:129], v[58:61], v[170:173], v[126:129]
	v_mfma_f32_16x16x32_bf16 v[122:125], v[74:77], v[170:173], v[122:125]
	v_mfma_f32_16x16x32_bf16 v[110:113], v[58:61], v[184:187], v[110:113]
	v_mfma_f32_16x16x32_bf16 v[106:109], v[74:77], v[184:187], v[106:109]
	v_mfma_f32_16x16x32_bf16 v[94:97], v[58:61], v[198:201], v[94:97]
	v_mfma_f32_16x16x32_bf16 v[90:93], v[74:77], v[198:201], v[90:93]
	v_mfma_f32_16x16x32_bf16 v[150:153], v[62:65], v[166:169], v[150:153]
	v_mfma_f32_16x16x32_bf16 v[146:149], v[78:81], v[166:169], v[146:149]
	v_mfma_f32_16x16x32_bf16 v[126:129], v[62:65], v[174:177], v[126:129]
	v_mfma_f32_16x16x32_bf16 v[122:125], v[78:81], v[174:177], v[122:125]
	v_mfma_f32_16x16x32_bf16 v[110:113], v[62:65], v[194:197], v[110:113]
	v_mfma_f32_16x16x32_bf16 v[106:109], v[78:81], v[194:197], v[106:109]
	v_mfma_f32_16x16x32_bf16 v[94:97], v[62:65], v[202:205], v[94:97]
	v_mfma_f32_16x16x32_bf16 v[90:93], v[78:81], v[202:205], v[90:93]
	v_mfma_f32_16x16x32_bf16 v[138:141], v[130:133], v[162:165], v[138:141]
	v_mfma_f32_16x16x32_bf16 v[134:137], v[154:157], v[162:165], v[134:137]
	v_mfma_f32_16x16x32_bf16 v[118:121], v[130:133], v[170:173], v[118:121]
	v_mfma_f32_16x16x32_bf16 v[114:117], v[154:157], v[170:173], v[114:117]
	v_mfma_f32_16x16x32_bf16 v[102:105], v[130:133], v[184:187], v[102:105]
	v_mfma_f32_16x16x32_bf16 v[98:101], v[154:157], v[184:187], v[98:101]
	v_mfma_f32_16x16x32_bf16 v[86:89], v[130:133], v[198:201], v[86:89]
	v_mfma_f32_16x16x32_bf16 v[82:85], v[154:157], v[198:201], v[82:85]
	v_mfma_f32_16x16x32_bf16 v[138:141], v[142:145], v[166:169], v[138:141]
	v_mfma_f32_16x16x32_bf16 v[134:137], v[158:161], v[166:169], v[134:137]
	v_mfma_f32_16x16x32_bf16 v[118:121], v[142:145], v[174:177], v[118:121]
	v_mfma_f32_16x16x32_bf16 v[114:117], v[158:161], v[174:177], v[114:117]
	v_mfma_f32_16x16x32_bf16 v[102:105], v[142:145], v[194:197], v[102:105]
	v_mfma_f32_16x16x32_bf16 v[98:101], v[158:161], v[194:197], v[98:101]
	v_mfma_f32_16x16x32_bf16 v[86:89], v[142:145], v[202:205], v[86:89]
	v_mfma_f32_16x16x32_bf16 v[82:85], v[158:161], v[202:205], v[82:85]
	s_barrier
; #define PG8_STAGE(bufoff, gbase, voff) do { _Pragma("unroll") for (int _i = 0; _i < 2; ++_i) \
;         __builtin_amdgcn_global_load_lds((const unsigned*)((const char*)(gbase) + (voff)[_i]), (PG8_LAS unsigned*)(lds + (bufoff) + ldsw + _i * 8192), 16, 0, 0); } while (0)
; #define PG8_LDA(dst, b, h) do { _Pragma("unroll") for (int m = 0; m < 4; ++m) _Pragma("unroll") for (int k = 0; k < 2; ++k) dst[m][k] = *(const PG8_LAS bf16x8*)(lds + PG8_SA(b, h) + aoff + m * 2048 + k * 1024); } while (0)
; #define PG8_LDB(dst, b, h) do { _Pragma("unroll") for (int n = 0; n < 2; ++n) _Pragma("unroll") for (int k = 0; k < 2; ++k) dst[n][k] = *(const PG8_LAS bf16x8*)(lds + PG8_SB(b, h) + boff + n * 2048 + k * 1024); } while (0)
; #define PG8_WAIT_V(n) asm volatile("s_waitcnt vmcnt(" #n ")" ::: "memory")
; #define PG8_WAIT_L(n) asm volatile("s_waitcnt lgkmcnt(" #n ")" ::: "memory")
; #define PG8_WAIT_V_SEL(sel) asm volatile("s_cmp_eq_u32 %0, 0\n\ts_cbranch_scc1 .Lw8_%=\n\ts_waitcnt vmcnt(22)\n\ts_branch .Lwd_%=\n.Lw8_%=:\n\ts_waitcnt vmcnt(8)\n.Lwd_%=:" :: "s"(sel) : "memory", "scc")
; #define PG8_BAR __builtin_amdgcn_s_barrier()
; #define PG8_SCHED __builtin_amdgcn_sched_barrier(0)
;     ...
;             PG8_LDA(At, 0, 1); PG8_STAGE(PG8_SB(0, 0), b2, voffB); PG8_STAGE(PG8_SB(0, 1), b2 + hstep, voffB); PG8_STAGE(PG8_SA(0, 0), a2, voffA);
;             PG8_WAIT_V_SEL(relax);
;             PG8_WAIT_L(0); PG8_BAR; PG8_MMA(1, 0, At, B0); PG8_MMA(1, 1, At, B1); PG8_BAR; PG8_SCHED;
;             PG8_LDB(B0, 1, 0); PG8_LDB(B1, 1, 1); PG8_SCHED; PG8_LDA(At, 1, 0); PG8_STAGE(PG8_SA(0, 1), a2 + hstep, voffA);
;             PG8_WAIT_V(8); PG8_WAIT_L(0); PG8_BAR; PG8_MMA(0, 0, At, B0); PG8_MMA(0, 1, At, B1); PG8_BAR; PG8_SCHED;
	s_setprio 0
	s_add_i32 s8, s46, s90
	s_mov_b32 m0, s8
	ds_read_b128 v[162:165], v246 offset:16384
	ds_read_b128 v[166:169], v246 offset:17408
	ds_read_b128 v[170:173], v246 offset:18432
	ds_read_b128 v[174:177], v246 offset:19456
	ds_read_b128 v[184:187], v246 offset:20480
	ds_read_b128 v[194:197], v246 offset:21504
	ds_read_b128 v[198:201], v246 offset:22528
	ds_read_b128 v[202:205], v246 offset:23552
	global_load_lds_dwordx4 v182, s[80:81]
	s_add_i32 m0, s8, 0x2000
	s_add_u32 s8, s80, 0x158000
	s_addc_u32 s9, s81, 0
	s_add_i32 s46, s47, s90
	global_load_lds_dwordx4 v188, s[80:81]
	s_mov_b32 m0, s46
	s_nop 0
	global_load_lds_dwordx4 v182, s[8:9]
	s_add_i32 m0, s46, 0x2000
	s_nop 0
	global_load_lds_dwordx4 v188, s[8:9]
	s_mov_b32 m0, s91
	s_nop 0
	global_load_lds_dwordx4 v178, s[40:41]
	s_mov_b32 m0, s92
	s_nop 0
	global_load_lds_dwordx4 v180, s[40:41]
	s_waitcnt vmcnt(8)
	s_waitcnt lgkmcnt(0)
	s_setprio 1
	s_barrier
	v_mfma_f32_16x16x32_bf16 v[70:73], v[58:61], v[162:165], v[70:73]
	v_mfma_f32_16x16x32_bf16 v[66:69], v[74:77], v[162:165], v[66:69]
	v_mfma_f32_16x16x32_bf16 v[46:49], v[58:61], v[170:173], v[46:49]
	v_mfma_f32_16x16x32_bf16 v[42:45], v[74:77], v[170:173], v[42:45]
	v_mfma_f32_16x16x32_bf16 v[30:33], v[58:61], v[184:187], v[30:33]
	v_mfma_f32_16x16x32_bf16 v[26:29], v[74:77], v[184:187], v[26:29]
	v_mfma_f32_16x16x32_bf16 v[14:17], v[58:61], v[198:201], v[14:17]
	v_mfma_f32_16x16x32_bf16 v[10:13], v[74:77], v[198:201], v[10:13]
	v_mfma_f32_16x16x32_bf16 v[70:73], v[62:65], v[166:169], v[70:73]
	v_mfma_f32_16x16x32_bf16 v[66:69], v[78:81], v[166:169], v[66:69]
	v_mfma_f32_16x16x32_bf16 v[46:49], v[62:65], v[174:177], v[46:49]
	v_mfma_f32_16x16x32_bf16 v[42:45], v[78:81], v[174:177], v[42:45]
	v_mfma_f32_16x16x32_bf16 v[30:33], v[62:65], v[194:197], v[30:33]
	v_mfma_f32_16x16x32_bf16 v[26:29], v[78:81], v[194:197], v[26:29]
	v_mfma_f32_16x16x32_bf16 v[14:17], v[62:65], v[202:205], v[14:17]
	v_mfma_f32_16x16x32_bf16 v[10:13], v[78:81], v[202:205], v[10:13]
	v_mfma_f32_16x16x32_bf16 v[54:57], v[130:133], v[162:165], v[54:57]
	v_mfma_f32_16x16x32_bf16 v[50:53], v[154:157], v[162:165], v[50:53]
	v_mfma_f32_16x16x32_bf16 v[38:41], v[130:133], v[170:173], v[38:41]
	v_mfma_f32_16x16x32_bf16 v[34:37], v[154:157], v[170:173], v[34:37]
	v_mfma_f32_16x16x32_bf16 v[22:25], v[130:133], v[184:187], v[22:25]
	v_mfma_f32_16x16x32_bf16 v[18:21], v[154:157], v[184:187], v[18:21]
	v_mfma_f32_16x16x32_bf16 v[6:9], v[130:133], v[198:201], v[6:9]
	v_mfma_f32_16x16x32_bf16 v[2:5], v[154:157], v[198:201], v[2:5]
	v_mfma_f32_16x16x32_bf16 v[54:57], v[142:145], v[166:169], v[54:57]
	v_mfma_f32_16x16x32_bf16 v[50:53], v[158:161], v[166:169], v[50:53]
	v_mfma_f32_16x16x32_bf16 v[38:41], v[142:145], v[174:177], v[38:41]
	v_mfma_f32_16x16x32_bf16 v[34:37], v[158:161], v[174:177], v[34:37]
	v_mfma_f32_16x16x32_bf16 v[22:25], v[142:145], v[194:197], v[22:25]
	v_mfma_f32_16x16x32_bf16 v[18:21], v[158:161], v[194:197], v[18:21]
	v_mfma_f32_16x16x32_bf16 v[6:9], v[142:145], v[202:205], v[6:9]
	v_mfma_f32_16x16x32_bf16 v[2:5], v[158:161], v[202:205], v[2:5]
	s_barrier
	s_setprio 0
	s_add_i32 s46, 0, 0x18000
	s_add_i32 s47, 0, 0x1c000
	ds_read_b128 v[58:61], v206 offset:32768
	ds_read_b128 v[62:65], v206 offset:33792
	ds_read_b128 v[74:77], v206 offset:34816
	ds_read_b128 v[78:81], v206 offset:35840
	ds_read_b128 v[130:133], v206 offset:49152
	ds_read_b128 v[142:145], v206 offset:50176
	ds_read_b128 v[154:157], v206 offset:51200
	ds_read_b128 v[158:161], v206 offset:52224
	s_add_u32 s8, s40, 0x158000
	s_addc_u32 s9, s41, 0
	s_mov_b32 m0, s93
	ds_read_b128 v[162:165], v246 offset:32768
	ds_read_b128 v[166:169], v246 offset:33792
	ds_read_b128 v[170:173], v246 offset:34816
	ds_read_b128 v[174:177], v246 offset:35840
	ds_read_b128 v[184:187], v246 offset:36864
	ds_read_b128 v[194:197], v246 offset:37888
	ds_read_b128 v[198:201], v246 offset:38912
	ds_read_b128 v[202:205], v246 offset:39936
	global_load_lds_dwordx4 v178, s[8:9]
	s_mov_b32 m0, s94
	s_nop 0
	global_load_lds_dwordx4 v180, s[8:9]
	s_waitcnt vmcnt(8)
	s_waitcnt lgkmcnt(0)
	s_setprio 1
	s_barrier
; #define PG8_STAGE(bufoff, gbase, voff) do { _Pragma("unroll") for (int _i = 0; _i < 2; ++_i) \
;         __builtin_amdgcn_global_load_lds((const unsigned*)((const char*)(gbase) + (voff)[_i]), (PG8_LAS unsigned*)(lds + (bufoff) + ldsw + _i * 8192), 16, 0, 0); } while (0)
; #define PG8_LDA(dst, b, h) do { _Pragma("unroll") for (int m = 0; m < 4; ++m) _Pragma("unroll") for (int k = 0; k < 2; ++k) dst[m][k] = *(const PG8_LAS bf16x8*)(lds + PG8_SA(b, h) + aoff + m * 2048 + k * 1024); } while (0)
; #define PG8_WAIT_V(n) asm volatile("s_waitcnt vmcnt(" #n ")" ::: "memory")
; #define PG8_WAIT_L(n) asm volatile("s_waitcnt lgkmcnt(" #n ")" ::: "memory")
; #define PG8_BAR __builtin_amdgcn_s_barrier()
; #define PG8_SCHED __builtin_amdgcn_sched_barrier(0)
;     ...
;             PG8_WAIT_V(8); PG8_WAIT_L(0); PG8_BAR; PG8_MMA(0, 0, At, B0); PG8_MMA(0, 1, At, B1); PG8_BAR; PG8_SCHED;
;             PG8_LDA(At, 1, 1); PG8_STAGE(PG8_SB(1, 0), b3, voffB); PG8_STAGE(PG8_SB(1, 1), b3 + hstep, voffB); PG8_STAGE(PG8_SA(1, 0), a3, voffA);
;             PG8_WAIT_V(8); PG8_WAIT_L(0); PG8_BAR; PG8_MMA(1, 0, At, B0); PG8_MMA(1, 1, At, B1); PG8_BAR; PG8_SCHED;
	v_mfma_f32_16x16x32_bf16 v[150:153], v[58:61], v[162:165], v[150:153]
	v_mfma_f32_16x16x32_bf16 v[146:149], v[74:77], v[162:165], v[146:149]
	v_mfma_f32_16x16x32_bf16 v[126:129], v[58:61], v[170:173], v[126:129]
	v_mfma_f32_16x16x32_bf16 v[122:125], v[74:77], v[170:173], v[122:125]
	v_mfma_f32_16x16x32_bf16 v[110:113], v[58:61], v[184:187], v[110:113]
	v_mfma_f32_16x16x32_bf16 v[106:109], v[74:77], v[184:187], v[106:109]
	v_mfma_f32_16x16x32_bf16 v[94:97], v[58:61], v[198:201], v[94:97]
	v_mfma_f32_16x16x32_bf16 v[90:93], v[74:77], v[198:201], v[90:93]
	v_mfma_f32_16x16x32_bf16 v[150:153], v[62:65], v[166:169], v[150:153]
	v_mfma_f32_16x16x32_bf16 v[146:149], v[78:81], v[166:169], v[146:149]
	v_mfma_f32_16x16x32_bf16 v[126:129], v[62:65], v[174:177], v[126:129]
	v_mfma_f32_16x16x32_bf16 v[122:125], v[78:81], v[174:177], v[122:125]
	v_mfma_f32_16x16x32_bf16 v[110:113], v[62:65], v[194:197], v[110:113]
	v_mfma_f32_16x16x32_bf16 v[106:109], v[78:81], v[194:197], v[106:109]
	v_mfma_f32_16x16x32_bf16 v[94:97], v[62:65], v[202:205], v[94:97]
	v_mfma_f32_16x16x32_bf16 v[90:93], v[78:81], v[202:205], v[90:93]
	v_mfma_f32_16x16x32_bf16 v[138:141], v[130:133], v[162:165], v[138:141]
	v_mfma_f32_16x16x32_bf16 v[134:137], v[154:157], v[162:165], v[134:137]
	v_mfma_f32_16x16x32_bf16 v[118:121], v[130:133], v[170:173], v[118:121]
	v_mfma_f32_16x16x32_bf16 v[114:117], v[154:157], v[170:173], v[114:117]
	v_mfma_f32_16x16x32_bf16 v[102:105], v[130:133], v[184:187], v[102:105]
	v_mfma_f32_16x16x32_bf16 v[98:101], v[154:157], v[184:187], v[98:101]
	v_mfma_f32_16x16x32_bf16 v[86:89], v[130:133], v[198:201], v[86:89]
	v_mfma_f32_16x16x32_bf16 v[82:85], v[154:157], v[198:201], v[82:85]
	v_mfma_f32_16x16x32_bf16 v[138:141], v[142:145], v[166:169], v[138:141]
	v_mfma_f32_16x16x32_bf16 v[134:137], v[158:161], v[166:169], v[134:137]
	v_mfma_f32_16x16x32_bf16 v[118:121], v[142:145], v[174:177], v[118:121]
	v_mfma_f32_16x16x32_bf16 v[114:117], v[158:161], v[174:177], v[114:117]
	v_mfma_f32_16x16x32_bf16 v[102:105], v[142:145], v[194:197], v[102:105]
	v_mfma_f32_16x16x32_bf16 v[98:101], v[158:161], v[194:197], v[98:101]
	v_mfma_f32_16x16x32_bf16 v[86:89], v[142:145], v[202:205], v[86:89]
	v_mfma_f32_16x16x32_bf16 v[82:85], v[158:161], v[202:205], v[82:85]
	s_barrier
	s_setprio 0
	s_add_i32 s8, s46, s90
	s_mov_b32 m0, s8
	ds_read_b128 v[162:165], v246 offset:49152
	ds_read_b128 v[166:169], v246 offset:50176
	ds_read_b128 v[170:173], v246 offset:51200
	ds_read_b128 v[174:177], v246 offset:52224
	ds_read_b128 v[184:187], v246 offset:53248
	ds_read_b128 v[194:197], v246 offset:54272
	ds_read_b128 v[198:201], v246 offset:55296
	ds_read_b128 v[202:205], v246 offset:56320
	s_add_u32 s100, s80, 0x80
	s_addc_u32 s101, s81, 0
	global_load_lds_dwordx4 v182, s[100:101]
	s_add_i32 m0, s8, 0x2000
	s_add_u32 s8, s80, 0x158080
	s_addc_u32 s9, s81, 0
	s_add_i32 vcc_lo, s47, s90
	global_load_lds_dwordx4 v188, s[100:101]
	s_mov_b32 m0, vcc_lo
	s_nop 0
	global_load_lds_dwordx4 v182, s[8:9]
	s_add_i32 m0, vcc_lo, 0x2000
	s_nop 0
	global_load_lds_dwordx4 v188, s[8:9]
	s_mov_b32 m0, s31
	s_nop 0
	s_add_u32 s100, s40, 0x80
	s_addc_u32 s101, s41, 0
	global_load_lds_dwordx4 v178, s[100:101]
	s_mov_b32 m0, s56
	s_nop 0
	global_load_lds_dwordx4 v180, s[100:101]
	s_waitcnt vmcnt(8)
	s_waitcnt lgkmcnt(0)
	s_setprio 1
	s_barrier
	v_mfma_f32_16x16x32_bf16 v[70:73], v[58:61], v[162:165], v[70:73]
	v_mfma_f32_16x16x32_bf16 v[66:69], v[74:77], v[162:165], v[66:69]
	v_mfma_f32_16x16x32_bf16 v[46:49], v[58:61], v[170:173], v[46:49]
	v_mfma_f32_16x16x32_bf16 v[42:45], v[74:77], v[170:173], v[42:45]
	v_mfma_f32_16x16x32_bf16 v[30:33], v[58:61], v[184:187], v[30:33]
	v_mfma_f32_16x16x32_bf16 v[26:29], v[74:77], v[184:187], v[26:29]
	v_mfma_f32_16x16x32_bf16 v[14:17], v[58:61], v[198:201], v[14:17]
	v_mfma_f32_16x16x32_bf16 v[10:13], v[74:77], v[198:201], v[10:13]
	v_mfma_f32_16x16x32_bf16 v[70:73], v[62:65], v[166:169], v[70:73]
	v_mfma_f32_16x16x32_bf16 v[66:69], v[78:81], v[166:169], v[66:69]
	v_mfma_f32_16x16x32_bf16 v[46:49], v[62:65], v[174:177], v[46:49]
	v_mfma_f32_16x16x32_bf16 v[42:45], v[78:81], v[174:177], v[42:45]
	v_mfma_f32_16x16x32_bf16 v[30:33], v[62:65], v[194:197], v[30:33]
	v_mfma_f32_16x16x32_bf16 v[26:29], v[78:81], v[194:197], v[26:29]
	v_mfma_f32_16x16x32_bf16 v[14:17], v[62:65], v[202:205], v[14:17]
	v_mfma_f32_16x16x32_bf16 v[10:13], v[78:81], v[202:205], v[10:13]
	v_mfma_f32_16x16x32_bf16 v[54:57], v[130:133], v[162:165], v[54:57]
	v_mfma_f32_16x16x32_bf16 v[50:53], v[154:157], v[162:165], v[50:53]
	v_mfma_f32_16x16x32_bf16 v[38:41], v[130:133], v[170:173], v[38:41]
	v_mfma_f32_16x16x32_bf16 v[34:37], v[154:157], v[170:173], v[34:37]
	v_mfma_f32_16x16x32_bf16 v[22:25], v[130:133], v[184:187], v[22:25]
	v_mfma_f32_16x16x32_bf16 v[18:21], v[154:157], v[184:187], v[18:21]
	v_mfma_f32_16x16x32_bf16 v[6:9], v[130:133], v[198:201], v[6:9]
	v_mfma_f32_16x16x32_bf16 v[2:5], v[154:157], v[198:201], v[2:5]
	v_mfma_f32_16x16x32_bf16 v[54:57], v[142:145], v[166:169], v[54:57]
	v_mfma_f32_16x16x32_bf16 v[50:53], v[158:161], v[166:169], v[50:53]
	v_mfma_f32_16x16x32_bf16 v[38:41], v[142:145], v[174:177], v[38:41]
	v_mfma_f32_16x16x32_bf16 v[34:37], v[158:161], v[174:177], v[34:37]
	v_mfma_f32_16x16x32_bf16 v[22:25], v[142:145], v[194:197], v[22:25]
	v_mfma_f32_16x16x32_bf16 v[18:21], v[158:161], v[194:197], v[18:21]
	v_mfma_f32_16x16x32_bf16 v[6:9], v[142:145], v[202:205], v[6:9]
	v_mfma_f32_16x16x32_bf16 v[2:5], v[158:161], v[202:205], v[2:5]
	s_barrier
	s_setprio 0
	s_add_i32 s45, s45, 2
	s_add_u32 s37, s37, 0x100
	s_addc_u32 s44, s44, 0
	s_cmpk_gt_u32 s45, 0x53
	s_mov_b64 s[8:9], s[10:11]
	s_cbranch_scc0 .LBB0_1648
	s_and_b64 vcc, exec, s[76:77]
	s_cbranch_vccz .LBB0_1651
	s_barrier
